# GEMM K-loops: removed the back-to-back s_setprio 0 / s_setprio 1 pair in the middle of each 32-MFMA segment (priority stays 1 across the segment)
# speedup vs baseline: 1.0131x; 1.0101x over previous
; #define PG8_STAGE(bufoff, gbase, voff) do { _Pragma("unroll") for (int _i = 0; _i < 2; ++_i) \
;         __builtin_amdgcn_global_load_lds((const unsigned*)((const char*)(gbase) + (voff)[_i]), (PG8_LAS unsigned*)(lds + (bufoff) + ldsw + _i * 8192), 16, 0, 0); } while (0)
; #define PG8_LDA(dst, b, h) do { _Pragma("unroll") for (int m = 0; m < 4; ++m) _Pragma("unroll") for (int k = 0; k < 2; ++k) dst[m][k] = *(const PG8_LAS bf16x8*)(lds + PG8_SA(b, h) + aoff + m * 2048 + k * 1024); } while (0)
; #define PG8_MMA(ai, bj, At, Bt) do { __builtin_amdgcn_s_setprio(1); _Pragma("unroll") for (int m = 0; m < 4; ++m) _Pragma("unroll") for (int n = 0; n < 2; ++n) _Pragma("unroll") for (int k = 0; k < 2; ++k) \
;         acc[ai][bj][m][n] = __builtin_amdgcn_mfma_f32_16x16x32_bf16(Bt[n][k], At[m][k], acc[ai][bj][m][n], 0, 0, 0); __builtin_amdgcn_s_setprio(0); } while (0)
; #define PG8_WAIT_V(n) asm volatile("s_waitcnt vmcnt(" #n ")" ::: "memory")
; #define PG8_WAIT_L(n) asm volatile("s_waitcnt lgkmcnt(" #n ")" ::: "memory")
; #define PG8_BAR __builtin_amdgcn_s_barrier()
; #define PG8_SCHED __builtin_amdgcn_sched_barrier(0)
; template <class Epi, class Sched, bool ALIGN_EPI = false, bool SP2 = false>
; __device__ __forceinline__ void gemm_phase(PG8_LAS unsigned char* lds, const Gemm g, const Sched& S, const Epi& E) {
;     ...
;             PG8_WAIT_V(8); PG8_WAIT_L(0); PG8_BAR; PG8_MMA(0, 0, At, B0); PG8_MMA(0, 1, At, B1); PG8_BAR; PG8_SCHED;
;             PG8_LDA(At, 0, 1); PG8_STAGE(PG8_SB(0, 0), b2, voffB); PG8_STAGE(PG8_SB(0, 1), b2 + hstep, voffB); PG8_STAGE(PG8_SA(0, 0), a2, voffA);
;             PG8_WAIT_V(8); PG8_WAIT_L(0); PG8_BAR; PG8_MMA(1, 0, At, B0); PG8_MMA(1, 1, At, B1); PG8_BAR; PG8_SCHED;
.Lodin_noz:
	s_waitcnt vmcnt(8)
	s_waitcnt lgkmcnt(0)
	s_barrier
	s_setprio 1
	s_waitcnt lgkmcnt(0)
	v_mfma_f32_16x16x32_bf16 v[70:73], v[130:133], v[188:191], v[70:73]
	v_mfma_f32_16x16x32_bf16 v[66:69], v[158:161], v[188:191], v[66:69]
	v_mfma_f32_16x16x32_bf16 v[62:65], v[130:133], v[196:199], v[62:65]
	v_mfma_f32_16x16x32_bf16 v[58:61], v[158:161], v[196:199], v[58:61]
	v_mfma_f32_16x16x32_bf16 v[54:57], v[130:133], v[204:207], v[54:57]
	v_mfma_f32_16x16x32_bf16 v[50:53], v[158:161], v[204:207], v[50:53]
	v_mfma_f32_16x16x32_bf16 v[46:49], v[130:133], v[212:215], v[46:49]
	v_mfma_f32_16x16x32_bf16 v[42:45], v[158:161], v[212:215], v[42:45]
	v_mfma_f32_16x16x32_bf16 v[70:73], v[154:157], v[192:195], v[70:73]
	v_mfma_f32_16x16x32_bf16 v[66:69], v[162:165], v[192:195], v[66:69]
	v_mfma_f32_16x16x32_bf16 v[62:65], v[154:157], v[200:203], v[62:65]
	v_mfma_f32_16x16x32_bf16 v[58:61], v[162:165], v[200:203], v[58:61]
	v_mfma_f32_16x16x32_bf16 v[54:57], v[154:157], v[208:211], v[54:57]
	v_mfma_f32_16x16x32_bf16 v[50:53], v[162:165], v[208:211], v[50:53]
	v_mfma_f32_16x16x32_bf16 v[46:49], v[154:157], v[216:219], v[46:49]
	v_mfma_f32_16x16x32_bf16 v[42:45], v[162:165], v[216:219], v[42:45]
	v_mfma_f32_16x16x32_bf16 v[126:129], v[166:169], v[188:191], v[126:129]
	v_mfma_f32_16x16x32_bf16 v[122:125], v[180:183], v[188:191], v[122:125]
	v_mfma_f32_16x16x32_bf16 v[118:121], v[166:169], v[196:199], v[118:121]
	v_mfma_f32_16x16x32_bf16 v[114:117], v[180:183], v[196:199], v[114:117]
	v_mfma_f32_16x16x32_bf16 v[110:113], v[166:169], v[204:207], v[110:113]
	v_mfma_f32_16x16x32_bf16 v[106:109], v[180:183], v[204:207], v[106:109]
	v_mfma_f32_16x16x32_bf16 v[102:105], v[166:169], v[212:215], v[102:105]
	v_mfma_f32_16x16x32_bf16 v[98:101], v[180:183], v[212:215], v[98:101]
	v_mfma_f32_16x16x32_bf16 v[126:129], v[170:173], v[192:195], v[126:129]
	v_mfma_f32_16x16x32_bf16 v[122:125], v[184:187], v[192:195], v[122:125]
	v_mfma_f32_16x16x32_bf16 v[118:121], v[170:173], v[200:203], v[118:121]
	v_mfma_f32_16x16x32_bf16 v[114:117], v[184:187], v[200:203], v[114:117]
	v_mfma_f32_16x16x32_bf16 v[110:113], v[170:173], v[208:211], v[110:113]
	v_mfma_f32_16x16x32_bf16 v[106:109], v[184:187], v[208:211], v[106:109]
	v_mfma_f32_16x16x32_bf16 v[102:105], v[170:173], v[216:219], v[102:105]
	v_mfma_f32_16x16x32_bf16 v[98:101], v[184:187], v[216:219], v[98:101]
	s_setprio 0
	s_barrier
	s_add_i32 s55, s55, s39
	v_lshl_add_u64 v[146:147], s[30:31], 0, v[138:139]
	s_mov_b32 m0, s55
	ds_read_b128 v[188:191], v153 offset:16384
	ds_read_b128 v[192:195], v153 offset:17408
	ds_read_b128 v[196:199], v153 offset:18432
	ds_read_b128 v[200:203], v153 offset:19456
	ds_read_b128 v[204:207], v153 offset:20480
	ds_read_b128 v[208:211], v153 offset:21504
	ds_read_b128 v[212:215], v153 offset:22528
	ds_read_b128 v[216:219], v153 offset:23552
	global_load_lds_dwordx4 v[146:147], off
	s_add_i32 m0, s55, 0x2000
	s_add_u32 s56, s30, 0x40000
	v_lshl_add_u64 v[220:221], s[30:31], 0, v[134:135]
	s_addc_u32 s57, s31, 0
	s_add_i32 s55, s58, s39
	global_load_lds_dwordx4 v[220:221], off
	v_lshl_add_u64 v[222:223], s[56:57], 0, v[138:139]
	s_mov_b32 m0, s55
	v_lshl_add_u64 v[228:229], s[34:35], 0, v[136:137]
	global_load_lds_dwordx4 v[222:223], off
	v_lshl_add_u64 v[222:223], s[56:57], 0, v[134:135]
	s_add_i32 m0, s55, 0x2000
	s_nop 0
	global_load_lds_dwordx4 v[222:223], off
	v_lshl_add_u64 v[222:223], s[34:35], 0, v[140:141]
	s_mov_b32 m0, s40
	s_nop 0
	global_load_lds_dwordx4 v[222:223], off
	s_mov_b32 m0, s41
	s_nop 0
	global_load_lds_dwordx4 v[228:229], off
	s_waitcnt vmcnt(8)
	s_waitcnt lgkmcnt(0)
	s_barrier
	s_setprio 1
	s_waitcnt lgkmcnt(0)
	v_mfma_f32_16x16x32_bf16 v[30:33], v[130:133], v[188:191], v[30:33]
	v_mfma_f32_16x16x32_bf16 v[26:29], v[158:161], v[188:191], v[26:29]
	v_mfma_f32_16x16x32_bf16 v[22:25], v[130:133], v[196:199], v[22:25]
	v_mfma_f32_16x16x32_bf16 v[18:21], v[158:161], v[196:199], v[18:21]
	v_mfma_f32_16x16x32_bf16 v[14:17], v[130:133], v[204:207], v[14:17]
	v_mfma_f32_16x16x32_bf16 v[10:13], v[158:161], v[204:207], v[10:13]
	v_mfma_f32_16x16x32_bf16 v[6:9], v[130:133], v[212:215], v[6:9]
	v_mfma_f32_16x16x32_bf16 v[2:5], v[158:161], v[212:215], v[2:5]
	v_mfma_f32_16x16x32_bf16 v[30:33], v[154:157], v[192:195], v[30:33]
	v_mfma_f32_16x16x32_bf16 v[26:29], v[162:165], v[192:195], v[26:29]
	v_mfma_f32_16x16x32_bf16 v[22:25], v[154:157], v[200:203], v[22:25]
	v_mfma_f32_16x16x32_bf16 v[18:21], v[162:165], v[200:203], v[18:21]
	v_mfma_f32_16x16x32_bf16 v[14:17], v[154:157], v[208:211], v[14:17]
	v_mfma_f32_16x16x32_bf16 v[10:13], v[162:165], v[208:211], v[10:13]
	v_mfma_f32_16x16x32_bf16 v[6:9], v[154:157], v[216:219], v[6:9]
	v_mfma_f32_16x16x32_bf16 v[2:5], v[162:165], v[216:219], v[2:5]
	v_mfma_f32_16x16x32_bf16 v[94:97], v[166:169], v[188:191], v[94:97]
	v_mfma_f32_16x16x32_bf16 v[90:93], v[180:183], v[188:191], v[90:93]
	v_mfma_f32_16x16x32_bf16 v[86:89], v[166:169], v[196:199], v[86:89]
	v_mfma_f32_16x16x32_bf16 v[82:85], v[180:183], v[196:199], v[82:85]
	v_mfma_f32_16x16x32_bf16 v[78:81], v[166:169], v[204:207], v[78:81]
	v_mfma_f32_16x16x32_bf16 v[74:77], v[180:183], v[204:207], v[74:77]
	v_mfma_f32_16x16x32_bf16 v[38:41], v[166:169], v[212:215], v[38:41]
	v_mfma_f32_16x16x32_bf16 v[34:37], v[180:183], v[212:215], v[34:37]
	v_mfma_f32_16x16x32_bf16 v[94:97], v[170:173], v[192:195], v[94:97]
	v_mfma_f32_16x16x32_bf16 v[90:93], v[184:187], v[192:195], v[90:93]
	v_mfma_f32_16x16x32_bf16 v[86:89], v[170:173], v[200:203], v[86:89]
	v_mfma_f32_16x16x32_bf16 v[82:85], v[184:187], v[200:203], v[82:85]
	v_mfma_f32_16x16x32_bf16 v[78:81], v[170:173], v[208:211], v[78:81]
	v_mfma_f32_16x16x32_bf16 v[74:77], v[184:187], v[208:211], v[74:77]
	v_mfma_f32_16x16x32_bf16 v[38:41], v[170:173], v[216:219], v[38:41]
	v_mfma_f32_16x16x32_bf16 v[34:37], v[184:187], v[216:219], v[34:37]
	s_setprio 0
	s_barrier
; #define PG8_STAGE(bufoff, gbase, voff) do { _Pragma("unroll") for (int _i = 0; _i < 2; ++_i) \
;         __builtin_amdgcn_global_load_lds((const unsigned*)((const char*)(gbase) + (voff)[_i]), (PG8_LAS unsigned*)(lds + (bufoff) + ldsw + _i * 8192), 16, 0, 0); } while (0)
; #define PG8_LDA(dst, b, h) do { _Pragma("unroll") for (int m = 0; m < 4; ++m) _Pragma("unroll") for (int k = 0; k < 2; ++k) dst[m][k] = *(const PG8_LAS bf16x8*)(lds + PG8_SA(b, h) + aoff + m * 2048 + k * 1024); } while (0)
; #define PG8_LDB(dst, b, h) do { _Pragma("unroll") for (int n = 0; n < 2; ++n) _Pragma("unroll") for (int k = 0; k < 2; ++k) dst[n][k] = *(const PG8_LAS bf16x8*)(lds + PG8_SB(b, h) + boff + n * 2048 + k * 1024); } while (0)
; #define PG8_MMA(ai, bj, At, Bt) do { __builtin_amdgcn_s_setprio(1); _Pragma("unroll") for (int m = 0; m < 4; ++m) _Pragma("unroll") for (int n = 0; n < 2; ++n) _Pragma("unroll") for (int k = 0; k < 2; ++k) \
;         acc[ai][bj][m][n] = __builtin_amdgcn_mfma_f32_16x16x32_bf16(Bt[n][k], At[m][k], acc[ai][bj][m][n], 0, 0, 0); __builtin_amdgcn_s_setprio(0); } while (0)
; #define PG8_WAIT_V(n) asm volatile("s_waitcnt vmcnt(" #n ")" ::: "memory")
; #define PG8_WAIT_L(n) asm volatile("s_waitcnt lgkmcnt(" #n ")" ::: "memory")
; #define PG8_BAR __builtin_amdgcn_s_barrier()
; #define PG8_SCHED __builtin_amdgcn_sched_barrier(0)
; template <class Epi, class Sched, bool ALIGN_EPI = false, bool SP2 = false>
; __device__ __forceinline__ void gemm_phase(PG8_LAS unsigned char* lds, const Gemm g, const Sched& S, const Epi& E) {
;     ...
;             PG8_LDB(B0, 1, 0); PG8_LDB(B1, 1, 1); PG8_SCHED; PG8_LDA(At, 1, 0); PG8_STAGE(PG8_SA(0, 1), a2 + hstep, voffA);
;             PG8_WAIT_V(8); PG8_WAIT_L(0); PG8_BAR; PG8_MMA(0, 0, At, B0); PG8_MMA(0, 1, At, B1); PG8_BAR; PG8_SCHED;
	s_add_i32 s55, 0, 0x18000
	v_add_u32_e32 v148, s55, v151
	s_add_i32 s56, 0, 0x1c000
	ds_read_b128 v[130:133], v148
	ds_read_b128 v[154:157], v148 offset:1024
	ds_read_b128 v[158:161], v148 offset:2048
	ds_read_b128 v[162:165], v148 offset:3072
	v_add_u32_e32 v148, s56, v151
	ds_read_b128 v[166:169], v148
	ds_read_b128 v[170:173], v148 offset:1024
	ds_read_b128 v[180:183], v148 offset:2048
	ds_read_b128 v[184:187], v148 offset:3072
	s_add_u32 s34, s34, 0x40000
	s_addc_u32 s35, s35, 0
	s_mov_b32 m0, s42
	v_lshl_add_u64 v[230:231], s[34:35], 0, v[140:141]
	ds_read_b128 v[188:191], v153 offset:32768
	ds_read_b128 v[192:195], v153 offset:33792
	ds_read_b128 v[196:199], v153 offset:34816
	ds_read_b128 v[200:203], v153 offset:35840
	ds_read_b128 v[204:207], v153 offset:36864
	ds_read_b128 v[208:211], v153 offset:37888
	ds_read_b128 v[212:215], v153 offset:38912
	ds_read_b128 v[216:219], v153 offset:39936
	global_load_lds_dwordx4 v[230:231], off
	v_lshl_add_u64 v[230:231], s[34:35], 0, v[136:137]
	s_mov_b32 m0, s43
	s_nop 0
	global_load_lds_dwordx4 v[230:231], off
	s_waitcnt vmcnt(8)
	s_waitcnt lgkmcnt(0)
	s_barrier
	s_setprio 1
	s_waitcnt lgkmcnt(0)
	v_mfma_f32_16x16x32_bf16 v[70:73], v[130:133], v[188:191], v[70:73]
	v_mfma_f32_16x16x32_bf16 v[66:69], v[158:161], v[188:191], v[66:69]
	v_mfma_f32_16x16x32_bf16 v[62:65], v[130:133], v[196:199], v[62:65]
	v_mfma_f32_16x16x32_bf16 v[58:61], v[158:161], v[196:199], v[58:61]
	v_mfma_f32_16x16x32_bf16 v[54:57], v[130:133], v[204:207], v[54:57]
	v_mfma_f32_16x16x32_bf16 v[50:53], v[158:161], v[204:207], v[50:53]
	v_mfma_f32_16x16x32_bf16 v[46:49], v[130:133], v[212:215], v[46:49]
	v_mfma_f32_16x16x32_bf16 v[42:45], v[158:161], v[212:215], v[42:45]
	v_mfma_f32_16x16x32_bf16 v[70:73], v[154:157], v[192:195], v[70:73]
	v_mfma_f32_16x16x32_bf16 v[66:69], v[162:165], v[192:195], v[66:69]
	v_mfma_f32_16x16x32_bf16 v[62:65], v[154:157], v[200:203], v[62:65]
	v_mfma_f32_16x16x32_bf16 v[58:61], v[162:165], v[200:203], v[58:61]
	v_mfma_f32_16x16x32_bf16 v[54:57], v[154:157], v[208:211], v[54:57]
	v_mfma_f32_16x16x32_bf16 v[50:53], v[162:165], v[208:211], v[50:53]
	v_mfma_f32_16x16x32_bf16 v[46:49], v[154:157], v[216:219], v[46:49]
	v_mfma_f32_16x16x32_bf16 v[42:45], v[162:165], v[216:219], v[42:45]
	v_mfma_f32_16x16x32_bf16 v[126:129], v[166:169], v[188:191], v[126:129]
	v_mfma_f32_16x16x32_bf16 v[122:125], v[180:183], v[188:191], v[122:125]
	v_mfma_f32_16x16x32_bf16 v[118:121], v[166:169], v[196:199], v[118:121]
	v_mfma_f32_16x16x32_bf16 v[114:117], v[180:183], v[196:199], v[114:117]
	v_mfma_f32_16x16x32_bf16 v[110:113], v[166:169], v[204:207], v[110:113]
	v_mfma_f32_16x16x32_bf16 v[106:109], v[180:183], v[204:207], v[106:109]
	v_mfma_f32_16x16x32_bf16 v[102:105], v[166:169], v[212:215], v[102:105]
	v_mfma_f32_16x16x32_bf16 v[98:101], v[180:183], v[212:215], v[98:101]
	v_mfma_f32_16x16x32_bf16 v[126:129], v[170:173], v[192:195], v[126:129]
	v_mfma_f32_16x16x32_bf16 v[122:125], v[184:187], v[192:195], v[122:125]
	v_mfma_f32_16x16x32_bf16 v[118:121], v[170:173], v[200:203], v[118:121]
	v_mfma_f32_16x16x32_bf16 v[114:117], v[184:187], v[200:203], v[114:117]
	v_mfma_f32_16x16x32_bf16 v[110:113], v[170:173], v[208:211], v[110:113]
	v_mfma_f32_16x16x32_bf16 v[106:109], v[184:187], v[208:211], v[106:109]
	v_mfma_f32_16x16x32_bf16 v[102:105], v[170:173], v[216:219], v[102:105]
	v_mfma_f32_16x16x32_bf16 v[98:101], v[184:187], v[216:219], v[98:101]
	s_setprio 0
	s_barrier
; #define PG8_STAGE(bufoff, gbase, voff) do { _Pragma("unroll") for (int _i = 0; _i < 2; ++_i) \
;         __builtin_amdgcn_global_load_lds((const unsigned*)((const char*)(gbase) + (voff)[_i]), (PG8_LAS unsigned*)(lds + (bufoff) + ldsw + _i * 8192), 16, 0, 0); } while (0)
; #define PG8_LDA(dst, b, h) do { _Pragma("unroll") for (int m = 0; m < 4; ++m) _Pragma("unroll") for (int k = 0; k < 2; ++k) dst[m][k] = *(const PG8_LAS bf16x8*)(lds + PG8_SA(b, h) + aoff + m * 2048 + k * 1024); } while (0)
; #define PG8_MMA(ai, bj, At, Bt) do { __builtin_amdgcn_s_setprio(1); _Pragma("unroll") for (int m = 0; m < 4; ++m) _Pragma("unroll") for (int n = 0; n < 2; ++n) _Pragma("unroll") for (int k = 0; k < 2; ++k) \
;         acc[ai][bj][m][n] = __builtin_amdgcn_mfma_f32_16x16x32_bf16(Bt[n][k], At[m][k], acc[ai][bj][m][n], 0, 0, 0); __builtin_amdgcn_s_setprio(0); } while (0)
; #define PG8_WAIT_V(n) asm volatile("s_waitcnt vmcnt(" #n ")" ::: "memory")
; #define PG8_WAIT_L(n) asm volatile("s_waitcnt lgkmcnt(" #n ")" ::: "memory")
; #define PG8_BAR __builtin_amdgcn_s_barrier()
; #define PG8_SCHED __builtin_amdgcn_sched_barrier(0)
; template <class Epi, class Sched, bool ALIGN_EPI = false, bool SP2 = false>
; __device__ __forceinline__ void gemm_phase(PG8_LAS unsigned char* lds, const Gemm g, const Sched& S, const Epi& E) {
;     ...
;         for (int t = 0; t < nt; t += 2) {
;     ...
;             PG8_LDA(At, 1, 1); PG8_STAGE(PG8_SB(1, 0), b3, voffB); PG8_STAGE(PG8_SB(1, 1), b3 + hstep, voffB); PG8_STAGE(PG8_SA(1, 0), a3, voffA);
;             PG8_WAIT_V(8); PG8_WAIT_L(0); PG8_BAR; PG8_MMA(1, 0, At, B0); PG8_MMA(1, 1, At, B1); PG8_BAR; PG8_SCHED;
	s_add_i32 s34, s55, s39
	v_lshl_add_u64 v[146:147], v[146:147], 0, s[96:97]
	s_mov_b32 m0, s34
	ds_read_b128 v[188:191], v153 offset:49152
	ds_read_b128 v[192:195], v153 offset:50176
	ds_read_b128 v[196:199], v153 offset:51200
	ds_read_b128 v[200:203], v153 offset:52224
	ds_read_b128 v[204:207], v153 offset:53248
	ds_read_b128 v[208:211], v153 offset:54272
	ds_read_b128 v[212:215], v153 offset:55296
	ds_read_b128 v[216:219], v153 offset:56320
	global_load_lds_dwordx4 v[146:147], off
	s_add_i32 m0, s34, 0x2000
	s_add_u32 s30, s30, 0x40080
	v_lshl_add_u64 v[146:147], v[220:221], 0, s[96:97]
	s_addc_u32 s31, s31, 0
	s_add_i32 s34, s56, s39
	global_load_lds_dwordx4 v[146:147], off
	v_lshl_add_u64 v[146:147], s[30:31], 0, v[138:139]
	s_mov_b32 m0, s34
	s_nop 0
	global_load_lds_dwordx4 v[146:147], off
	v_lshl_add_u64 v[146:147], s[30:31], 0, v[134:135]
	s_add_i32 m0, s34, 0x2000
	s_nop 0
	global_load_lds_dwordx4 v[146:147], off
	v_lshl_add_u64 v[146:147], v[222:223], 0, s[96:97]
	s_mov_b32 m0, s48
	s_nop 0
	global_load_lds_dwordx4 v[146:147], off
	v_lshl_add_u64 v[146:147], v[228:229], 0, s[96:97]
	s_mov_b32 m0, s49
	s_nop 0
	global_load_lds_dwordx4 v[146:147], off
	s_waitcnt vmcnt(8)
	s_waitcnt lgkmcnt(0)
	s_barrier
	s_setprio 1
	s_waitcnt lgkmcnt(0)
	v_mfma_f32_16x16x32_bf16 v[30:33], v[130:133], v[188:191], v[30:33]
	v_mfma_f32_16x16x32_bf16 v[26:29], v[158:161], v[188:191], v[26:29]
	v_mfma_f32_16x16x32_bf16 v[22:25], v[130:133], v[196:199], v[22:25]
	v_mfma_f32_16x16x32_bf16 v[18:21], v[158:161], v[196:199], v[18:21]
	v_mfma_f32_16x16x32_bf16 v[14:17], v[130:133], v[204:207], v[14:17]
	v_mfma_f32_16x16x32_bf16 v[10:13], v[158:161], v[204:207], v[10:13]
	v_mfma_f32_16x16x32_bf16 v[6:9], v[130:133], v[212:215], v[6:9]
	v_mfma_f32_16x16x32_bf16 v[2:5], v[158:161], v[212:215], v[2:5]
	v_mfma_f32_16x16x32_bf16 v[30:33], v[154:157], v[192:195], v[30:33]
	v_mfma_f32_16x16x32_bf16 v[26:29], v[162:165], v[192:195], v[26:29]
	v_mfma_f32_16x16x32_bf16 v[22:25], v[154:157], v[200:203], v[22:25]
	v_mfma_f32_16x16x32_bf16 v[18:21], v[162:165], v[200:203], v[18:21]
	v_mfma_f32_16x16x32_bf16 v[14:17], v[154:157], v[208:211], v[14:17]
	v_mfma_f32_16x16x32_bf16 v[10:13], v[162:165], v[208:211], v[10:13]
	v_mfma_f32_16x16x32_bf16 v[6:9], v[154:157], v[216:219], v[6:9]
	v_mfma_f32_16x16x32_bf16 v[2:5], v[162:165], v[216:219], v[2:5]
	v_mfma_f32_16x16x32_bf16 v[94:97], v[166:169], v[188:191], v[94:97]
	v_mfma_f32_16x16x32_bf16 v[90:93], v[180:183], v[188:191], v[90:93]
	v_mfma_f32_16x16x32_bf16 v[86:89], v[166:169], v[196:199], v[86:89]
	v_mfma_f32_16x16x32_bf16 v[82:85], v[180:183], v[196:199], v[82:85]
	v_mfma_f32_16x16x32_bf16 v[78:81], v[166:169], v[204:207], v[78:81]
	v_mfma_f32_16x16x32_bf16 v[74:77], v[180:183], v[204:207], v[74:77]
	v_mfma_f32_16x16x32_bf16 v[38:41], v[166:169], v[212:215], v[38:41]
	v_mfma_f32_16x16x32_bf16 v[34:37], v[180:183], v[212:215], v[34:37]
	v_mfma_f32_16x16x32_bf16 v[94:97], v[170:173], v[192:195], v[94:97]
	v_mfma_f32_16x16x32_bf16 v[90:93], v[184:187], v[192:195], v[90:93]
	v_mfma_f32_16x16x32_bf16 v[86:89], v[170:173], v[200:203], v[86:89]
	v_mfma_f32_16x16x32_bf16 v[82:85], v[184:187], v[200:203], v[82:85]
	v_mfma_f32_16x16x32_bf16 v[78:81], v[170:173], v[208:211], v[78:81]
	v_mfma_f32_16x16x32_bf16 v[74:77], v[184:187], v[208:211], v[74:77]
	v_mfma_f32_16x16x32_bf16 v[38:41], v[170:173], v[216:219], v[38:41]
	v_mfma_f32_16x16x32_bf16 v[34:37], v[184:187], v[216:219], v[34:37]
	s_setprio 0
	s_barrier
	s_add_i32 s54, s54, 2
	s_add_u32 s28, s28, 0x100
	s_addc_u32 s29, s29, 0
	s_add_u32 s52, s52, 0x100
	s_addc_u32 s53, s53, 0
	s_cmp_gt_u32 s54, 13
	s_cbranch_scc0 .LBB0_185
	s_and_b64 vcc, exec, s[16:17]
	s_cbranch_vccz .LBB0_188
	s_barrier

; #define PG8_STAGE(bufoff, gbase, voff) do { _Pragma("unroll") for (int _i = 0; _i < 2; ++_i) \
;         __builtin_amdgcn_global_load_lds((const unsigned*)((const char*)(gbase) + (voff)[_i]), (PG8_LAS unsigned*)(lds + (bufoff) + ldsw + _i * 8192), 16, 0, 0); } while (0)
; #define PG8_LDA(dst, b, h) do { _Pragma("unroll") for (int m = 0; m < 4; ++m) _Pragma("unroll") for (int k = 0; k < 2; ++k) dst[m][k] = *(const PG8_LAS bf16x8*)(lds + PG8_SA(b, h) + aoff + m * 2048 + k * 1024); } while (0)
; #define PG8_MMA(ai, bj, At, Bt) do { __builtin_amdgcn_s_setprio(1); _Pragma("unroll") for (int m = 0; m < 4; ++m) _Pragma("unroll") for (int n = 0; n < 2; ++n) _Pragma("unroll") for (int k = 0; k < 2; ++k) \
;         acc[ai][bj][m][n] = __builtin_amdgcn_mfma_f32_16x16x32_bf16(Bt[n][k], At[m][k], acc[ai][bj][m][n], 0, 0, 0); __builtin_amdgcn_s_setprio(0); } while (0)
; #define PG8_WAIT_V(n) asm volatile("s_waitcnt vmcnt(" #n ")" ::: "memory")
; #define PG8_WAIT_L(n) asm volatile("s_waitcnt lgkmcnt(" #n ")" ::: "memory")
; #define PG8_BAR __builtin_amdgcn_s_barrier()
; #define PG8_SCHED __builtin_amdgcn_sched_barrier(0)
; template <class Epi, class Sched, bool ALIGN_EPI = false, bool SP2 = false>
; __device__ __forceinline__ void gemm_phase(PG8_LAS unsigned char* lds, const Gemm g, const Sched& S, const Epi& E) {
;     ...
;             PG8_WAIT_V(8); PG8_WAIT_L(0); PG8_BAR; PG8_MMA(0, 0, At, B0); PG8_MMA(0, 1, At, B1); PG8_BAR; PG8_SCHED;
;             PG8_LDA(At, 0, 1); PG8_STAGE(PG8_SB(0, 0), b2, voffB); PG8_STAGE(PG8_SB(0, 1), b2 + hstep, voffB); PG8_STAGE(PG8_SA(0, 0), a2, voffA);
;             PG8_WAIT_V(8); PG8_WAIT_L(0); PG8_BAR; PG8_MMA(1, 0, At, B0); PG8_MMA(1, 1, At, B1); PG8_BAR; PG8_SCHED;
.Lodout_noz:
	s_waitcnt vmcnt(8)
	s_waitcnt lgkmcnt(0)
	s_barrier
	s_setprio 1
	s_waitcnt lgkmcnt(0)
	v_mfma_f32_16x16x32_bf16 v[158:161], v[66:69], v[162:165], v[158:161]
	v_mfma_f32_16x16x32_bf16 v[154:157], v[82:85], v[162:165], v[154:157]
	v_mfma_f32_16x16x32_bf16 v[142:145], v[66:69], v[188:191], v[142:145]
	v_mfma_f32_16x16x32_bf16 v[138:141], v[82:85], v[188:191], v[138:141]
	v_mfma_f32_16x16x32_bf16 v[114:117], v[66:69], v[196:199], v[114:117]
	v_mfma_f32_16x16x32_bf16 v[110:113], v[82:85], v[196:199], v[110:113]
	v_mfma_f32_16x16x32_bf16 v[90:93], v[66:69], v[210:213], v[90:93]
	v_mfma_f32_16x16x32_bf16 v[86:89], v[82:85], v[210:213], v[86:89]
	v_mfma_f32_16x16x32_bf16 v[158:161], v[70:73], v[166:169], v[158:161]
	v_mfma_f32_16x16x32_bf16 v[154:157], v[94:97], v[166:169], v[154:157]
	v_mfma_f32_16x16x32_bf16 v[142:145], v[70:73], v[192:195], v[142:145]
	v_mfma_f32_16x16x32_bf16 v[138:141], v[94:97], v[192:195], v[138:141]
	v_mfma_f32_16x16x32_bf16 v[114:117], v[70:73], v[206:209], v[114:117]
	v_mfma_f32_16x16x32_bf16 v[110:113], v[94:97], v[206:209], v[110:113]
	v_mfma_f32_16x16x32_bf16 v[90:93], v[70:73], v[214:217], v[90:93]
	v_mfma_f32_16x16x32_bf16 v[86:89], v[94:97], v[214:217], v[86:89]
	v_mfma_f32_16x16x32_bf16 v[150:153], v[106:109], v[162:165], v[150:153]
	v_mfma_f32_16x16x32_bf16 v[146:149], v[130:133], v[162:165], v[146:149]
	v_mfma_f32_16x16x32_bf16 v[126:129], v[106:109], v[188:191], v[126:129]
	v_mfma_f32_16x16x32_bf16 v[122:125], v[130:133], v[188:191], v[122:125]
	v_mfma_f32_16x16x32_bf16 v[102:105], v[106:109], v[196:199], v[102:105]
	v_mfma_f32_16x16x32_bf16 v[98:101], v[130:133], v[196:199], v[98:101]
	v_mfma_f32_16x16x32_bf16 v[78:81], v[106:109], v[210:213], v[78:81]
	v_mfma_f32_16x16x32_bf16 v[74:77], v[130:133], v[210:213], v[74:77]
	v_mfma_f32_16x16x32_bf16 v[150:153], v[118:121], v[166:169], v[150:153]
	v_mfma_f32_16x16x32_bf16 v[146:149], v[134:137], v[166:169], v[146:149]
	v_mfma_f32_16x16x32_bf16 v[126:129], v[118:121], v[192:195], v[126:129]
	v_mfma_f32_16x16x32_bf16 v[122:125], v[134:137], v[192:195], v[122:125]
	v_mfma_f32_16x16x32_bf16 v[102:105], v[118:121], v[206:209], v[102:105]
	v_mfma_f32_16x16x32_bf16 v[98:101], v[134:137], v[206:209], v[98:101]
	v_mfma_f32_16x16x32_bf16 v[78:81], v[118:121], v[214:217], v[78:81]
	v_mfma_f32_16x16x32_bf16 v[74:77], v[134:137], v[214:217], v[74:77]
	s_setprio 0
	s_barrier
	s_add_i32 s56, s56, s42
	v_lshl_add_u64 v[200:201], s[12:13], 0, v[180:181]
	s_mov_b32 m0, s56
	ds_read_b128 v[162:165], v204 offset:16384
	ds_read_b128 v[166:169], v204 offset:17408
	ds_read_b128 v[188:191], v204 offset:18432
	ds_read_b128 v[192:195], v204 offset:19456
	ds_read_b128 v[196:199], v204 offset:20480
	ds_read_b128 v[206:209], v204 offset:21504
	ds_read_b128 v[210:213], v204 offset:22528
	ds_read_b128 v[214:217], v204 offset:23552
	global_load_lds_dwordx4 v[200:201], off
	s_add_i32 m0, s56, 0x2000
	s_add_u32 s56, s12, 0x40000
	v_lshl_add_u64 v[218:219], s[12:13], 0, v[170:171]
	s_addc_u32 s57, s13, 0
	s_add_i32 s58, s58, s42
	global_load_lds_dwordx4 v[218:219], off
	v_lshl_add_u64 v[220:221], s[56:57], 0, v[180:181]
	s_mov_b32 m0, s58
	v_lshl_add_u64 v[222:223], s[36:37], 0, v[172:173]
	global_load_lds_dwordx4 v[220:221], off
	v_lshl_add_u64 v[220:221], s[56:57], 0, v[170:171]
	s_add_i32 m0, s58, 0x2000
	s_nop 0
	global_load_lds_dwordx4 v[220:221], off
	v_lshl_add_u64 v[220:221], s[36:37], 0, v[182:183]
	s_mov_b32 m0, s43
	s_nop 0
	global_load_lds_dwordx4 v[220:221], off
	s_mov_b32 m0, s44
	s_nop 0
	global_load_lds_dwordx4 v[222:223], off
	s_waitcnt vmcnt(8)
	s_waitcnt lgkmcnt(0)
	s_barrier
	s_setprio 1
	s_waitcnt lgkmcnt(0)
	v_mfma_f32_16x16x32_bf16 v[62:65], v[66:69], v[162:165], v[62:65]
	v_mfma_f32_16x16x32_bf16 v[58:61], v[82:85], v[162:165], v[58:61]
	v_mfma_f32_16x16x32_bf16 v[46:49], v[66:69], v[188:191], v[46:49]
	v_mfma_f32_16x16x32_bf16 v[42:45], v[82:85], v[188:191], v[42:45]
	v_mfma_f32_16x16x32_bf16 v[30:33], v[66:69], v[196:199], v[30:33]
	v_mfma_f32_16x16x32_bf16 v[26:29], v[82:85], v[196:199], v[26:29]
	v_mfma_f32_16x16x32_bf16 v[14:17], v[66:69], v[210:213], v[14:17]
	v_mfma_f32_16x16x32_bf16 v[10:13], v[82:85], v[210:213], v[10:13]
	v_mfma_f32_16x16x32_bf16 v[62:65], v[70:73], v[166:169], v[62:65]
	v_mfma_f32_16x16x32_bf16 v[58:61], v[94:97], v[166:169], v[58:61]
	v_mfma_f32_16x16x32_bf16 v[46:49], v[70:73], v[192:195], v[46:49]
	v_mfma_f32_16x16x32_bf16 v[42:45], v[94:97], v[192:195], v[42:45]
	v_mfma_f32_16x16x32_bf16 v[30:33], v[70:73], v[206:209], v[30:33]
	v_mfma_f32_16x16x32_bf16 v[26:29], v[94:97], v[206:209], v[26:29]
	v_mfma_f32_16x16x32_bf16 v[14:17], v[70:73], v[214:217], v[14:17]
	v_mfma_f32_16x16x32_bf16 v[10:13], v[94:97], v[214:217], v[10:13]
	v_mfma_f32_16x16x32_bf16 v[54:57], v[106:109], v[162:165], v[54:57]
	v_mfma_f32_16x16x32_bf16 v[50:53], v[130:133], v[162:165], v[50:53]
	v_mfma_f32_16x16x32_bf16 v[38:41], v[106:109], v[188:191], v[38:41]
	v_mfma_f32_16x16x32_bf16 v[34:37], v[130:133], v[188:191], v[34:37]
	v_mfma_f32_16x16x32_bf16 v[22:25], v[106:109], v[196:199], v[22:25]
	v_mfma_f32_16x16x32_bf16 v[18:21], v[130:133], v[196:199], v[18:21]
	v_mfma_f32_16x16x32_bf16 v[6:9], v[106:109], v[210:213], v[6:9]
	v_mfma_f32_16x16x32_bf16 v[2:5], v[130:133], v[210:213], v[2:5]
	v_mfma_f32_16x16x32_bf16 v[54:57], v[118:121], v[166:169], v[54:57]
	v_mfma_f32_16x16x32_bf16 v[50:53], v[134:137], v[166:169], v[50:53]
	v_mfma_f32_16x16x32_bf16 v[38:41], v[118:121], v[192:195], v[38:41]
	v_mfma_f32_16x16x32_bf16 v[34:37], v[134:137], v[192:195], v[34:37]
	v_mfma_f32_16x16x32_bf16 v[22:25], v[118:121], v[206:209], v[22:25]
	v_mfma_f32_16x16x32_bf16 v[18:21], v[134:137], v[206:209], v[18:21]
	v_mfma_f32_16x16x32_bf16 v[6:9], v[118:121], v[214:217], v[6:9]
	v_mfma_f32_16x16x32_bf16 v[2:5], v[134:137], v[214:217], v[2:5]
	s_setprio 0
	s_barrier
; #define PG8_STAGE(bufoff, gbase, voff) do { _Pragma("unroll") for (int _i = 0; _i < 2; ++_i) \
;         __builtin_amdgcn_global_load_lds((const unsigned*)((const char*)(gbase) + (voff)[_i]), (PG8_LAS unsigned*)(lds + (bufoff) + ldsw + _i * 8192), 16, 0, 0); } while (0)
; #define PG8_LDA(dst, b, h) do { _Pragma("unroll") for (int m = 0; m < 4; ++m) _Pragma("unroll") for (int k = 0; k < 2; ++k) dst[m][k] = *(const PG8_LAS bf16x8*)(lds + PG8_SA(b, h) + aoff + m * 2048 + k * 1024); } while (0)
; #define PG8_LDB(dst, b, h) do { _Pragma("unroll") for (int n = 0; n < 2; ++n) _Pragma("unroll") for (int k = 0; k < 2; ++k) dst[n][k] = *(const PG8_LAS bf16x8*)(lds + PG8_SB(b, h) + boff + n * 2048 + k * 1024); } while (0)
; #define PG8_MMA(ai, bj, At, Bt) do { __builtin_amdgcn_s_setprio(1); _Pragma("unroll") for (int m = 0; m < 4; ++m) _Pragma("unroll") for (int n = 0; n < 2; ++n) _Pragma("unroll") for (int k = 0; k < 2; ++k) \
;         acc[ai][bj][m][n] = __builtin_amdgcn_mfma_f32_16x16x32_bf16(Bt[n][k], At[m][k], acc[ai][bj][m][n], 0, 0, 0); __builtin_amdgcn_s_setprio(0); } while (0)
; #define PG8_WAIT_V(n) asm volatile("s_waitcnt vmcnt(" #n ")" ::: "memory")
; #define PG8_WAIT_L(n) asm volatile("s_waitcnt lgkmcnt(" #n ")" ::: "memory")
; #define PG8_BAR __builtin_amdgcn_s_barrier()
; #define PG8_SCHED __builtin_amdgcn_sched_barrier(0)
; template <class Epi, class Sched, bool ALIGN_EPI = false, bool SP2 = false>
; __device__ __forceinline__ void gemm_phase(PG8_LAS unsigned char* lds, const Gemm g, const Sched& S, const Epi& E) {
;     ...
;             PG8_LDB(B0, 1, 0); PG8_LDB(B1, 1, 1); PG8_SCHED; PG8_LDA(At, 1, 0); PG8_STAGE(PG8_SA(0, 1), a2 + hstep, voffA);
;             PG8_WAIT_V(8); PG8_WAIT_L(0); PG8_BAR; PG8_MMA(0, 0, At, B0); PG8_MMA(0, 1, At, B1); PG8_BAR; PG8_SCHED;
	s_add_i32 s56, 0, 0x18000
	s_add_i32 s57, 0, 0x1c000
	v_add_u32_e32 v94, s56, v203
	v_add_u32_e32 v134, s57, v203
	ds_read_b128 v[66:69], v94
	ds_read_b128 v[70:73], v94 offset:1024
	ds_read_b128 v[82:85], v94 offset:2048
	ds_read_b128 v[94:97], v94 offset:3072
	ds_read_b128 v[106:109], v134
	ds_read_b128 v[118:121], v134 offset:1024
	ds_read_b128 v[130:133], v134 offset:2048
	ds_read_b128 v[134:137], v134 offset:3072
	s_add_u32 s36, s36, 0x40000
	s_addc_u32 s37, s37, 0
	s_mov_b32 m0, s45
	v_lshl_add_u64 v[228:229], s[36:37], 0, v[182:183]
	ds_read_b128 v[162:165], v204 offset:32768
	ds_read_b128 v[166:169], v204 offset:33792
	ds_read_b128 v[188:191], v204 offset:34816
	ds_read_b128 v[192:195], v204 offset:35840
	ds_read_b128 v[196:199], v204 offset:36864
	ds_read_b128 v[206:209], v204 offset:37888
	ds_read_b128 v[210:213], v204 offset:38912
	ds_read_b128 v[214:217], v204 offset:39936
	global_load_lds_dwordx4 v[228:229], off
	v_lshl_add_u64 v[228:229], s[36:37], 0, v[172:173]
	s_mov_b32 m0, s46
	s_nop 0
	global_load_lds_dwordx4 v[228:229], off
	s_waitcnt vmcnt(8)
	s_waitcnt lgkmcnt(0)
	s_barrier
	s_setprio 1
	s_waitcnt lgkmcnt(0)
	v_mfma_f32_16x16x32_bf16 v[158:161], v[66:69], v[162:165], v[158:161]
	v_mfma_f32_16x16x32_bf16 v[154:157], v[82:85], v[162:165], v[154:157]
	v_mfma_f32_16x16x32_bf16 v[142:145], v[66:69], v[188:191], v[142:145]
	v_mfma_f32_16x16x32_bf16 v[138:141], v[82:85], v[188:191], v[138:141]
	v_mfma_f32_16x16x32_bf16 v[114:117], v[66:69], v[196:199], v[114:117]
	v_mfma_f32_16x16x32_bf16 v[110:113], v[82:85], v[196:199], v[110:113]
	v_mfma_f32_16x16x32_bf16 v[90:93], v[66:69], v[210:213], v[90:93]
	v_mfma_f32_16x16x32_bf16 v[86:89], v[82:85], v[210:213], v[86:89]
	v_mfma_f32_16x16x32_bf16 v[158:161], v[70:73], v[166:169], v[158:161]
	v_mfma_f32_16x16x32_bf16 v[154:157], v[94:97], v[166:169], v[154:157]
	v_mfma_f32_16x16x32_bf16 v[142:145], v[70:73], v[192:195], v[142:145]
	v_mfma_f32_16x16x32_bf16 v[138:141], v[94:97], v[192:195], v[138:141]
	v_mfma_f32_16x16x32_bf16 v[114:117], v[70:73], v[206:209], v[114:117]
	v_mfma_f32_16x16x32_bf16 v[110:113], v[94:97], v[206:209], v[110:113]
	v_mfma_f32_16x16x32_bf16 v[90:93], v[70:73], v[214:217], v[90:93]
	v_mfma_f32_16x16x32_bf16 v[86:89], v[94:97], v[214:217], v[86:89]
	v_mfma_f32_16x16x32_bf16 v[150:153], v[106:109], v[162:165], v[150:153]
	v_mfma_f32_16x16x32_bf16 v[146:149], v[130:133], v[162:165], v[146:149]
	v_mfma_f32_16x16x32_bf16 v[126:129], v[106:109], v[188:191], v[126:129]
	v_mfma_f32_16x16x32_bf16 v[122:125], v[130:133], v[188:191], v[122:125]
	v_mfma_f32_16x16x32_bf16 v[102:105], v[106:109], v[196:199], v[102:105]
	v_mfma_f32_16x16x32_bf16 v[98:101], v[130:133], v[196:199], v[98:101]
	v_mfma_f32_16x16x32_bf16 v[78:81], v[106:109], v[210:213], v[78:81]
	v_mfma_f32_16x16x32_bf16 v[74:77], v[130:133], v[210:213], v[74:77]
	v_mfma_f32_16x16x32_bf16 v[150:153], v[118:121], v[166:169], v[150:153]
	v_mfma_f32_16x16x32_bf16 v[146:149], v[134:137], v[166:169], v[146:149]
	v_mfma_f32_16x16x32_bf16 v[126:129], v[118:121], v[192:195], v[126:129]
	v_mfma_f32_16x16x32_bf16 v[122:125], v[134:137], v[192:195], v[122:125]
	v_mfma_f32_16x16x32_bf16 v[102:105], v[118:121], v[206:209], v[102:105]
	v_mfma_f32_16x16x32_bf16 v[98:101], v[134:137], v[206:209], v[98:101]
	v_mfma_f32_16x16x32_bf16 v[78:81], v[118:121], v[214:217], v[78:81]
	v_mfma_f32_16x16x32_bf16 v[74:77], v[134:137], v[214:217], v[74:77]
	s_setprio 0
	s_barrier
; #define PG8_STAGE(bufoff, gbase, voff) do { _Pragma("unroll") for (int _i = 0; _i < 2; ++_i) \
;         __builtin_amdgcn_global_load_lds((const unsigned*)((const char*)(gbase) + (voff)[_i]), (PG8_LAS unsigned*)(lds + (bufoff) + ldsw + _i * 8192), 16, 0, 0); } while (0)
; #define PG8_LDA(dst, b, h) do { _Pragma("unroll") for (int m = 0; m < 4; ++m) _Pragma("unroll") for (int k = 0; k < 2; ++k) dst[m][k] = *(const PG8_LAS bf16x8*)(lds + PG8_SA(b, h) + aoff + m * 2048 + k * 1024); } while (0)
; #define PG8_MMA(ai, bj, At, Bt) do { __builtin_amdgcn_s_setprio(1); _Pragma("unroll") for (int m = 0; m < 4; ++m) _Pragma("unroll") for (int n = 0; n < 2; ++n) _Pragma("unroll") for (int k = 0; k < 2; ++k) \
;         acc[ai][bj][m][n] = __builtin_amdgcn_mfma_f32_16x16x32_bf16(Bt[n][k], At[m][k], acc[ai][bj][m][n], 0, 0, 0); __builtin_amdgcn_s_setprio(0); } while (0)
; #define PG8_WAIT_V(n) asm volatile("s_waitcnt vmcnt(" #n ")" ::: "memory")
; #define PG8_WAIT_L(n) asm volatile("s_waitcnt lgkmcnt(" #n ")" ::: "memory")
; #define PG8_BAR __builtin_amdgcn_s_barrier()
; #define PG8_SCHED __builtin_amdgcn_sched_barrier(0)
; template <class Epi, class Sched, bool ALIGN_EPI = false, bool SP2 = false>
; __device__ __forceinline__ void gemm_phase(PG8_LAS unsigned char* lds, const Gemm g, const Sched& S, const Epi& E) {
;     ...
;         for (int t = 0; t < nt; t += 2) {
;     ...
;             PG8_LDA(At, 1, 1); PG8_STAGE(PG8_SB(1, 0), b3, voffB); PG8_STAGE(PG8_SB(1, 1), b3 + hstep, voffB); PG8_STAGE(PG8_SA(1, 0), a3, voffA);
;             PG8_WAIT_V(8); PG8_WAIT_L(0); PG8_BAR; PG8_MMA(1, 0, At, B0); PG8_MMA(1, 1, At, B1); PG8_BAR; PG8_SCHED;
	s_add_i32 s36, s56, s42
	v_lshl_add_u64 v[200:201], v[200:201], 0, s[96:97]
	s_mov_b32 m0, s36
	ds_read_b128 v[162:165], v204 offset:49152
	ds_read_b128 v[166:169], v204 offset:50176
	ds_read_b128 v[188:191], v204 offset:51200
	ds_read_b128 v[192:195], v204 offset:52224
	ds_read_b128 v[196:199], v204 offset:53248
	ds_read_b128 v[206:209], v204 offset:54272
	ds_read_b128 v[210:213], v204 offset:55296
	ds_read_b128 v[214:217], v204 offset:56320
	global_load_lds_dwordx4 v[200:201], off
	s_add_i32 m0, s36, 0x2000
	s_add_u32 s12, s12, 0x40080
	v_lshl_add_u64 v[200:201], v[218:219], 0, s[96:97]
	s_addc_u32 s13, s13, 0
	s_add_i32 s36, s57, s42
	global_load_lds_dwordx4 v[200:201], off
	v_lshl_add_u64 v[200:201], s[12:13], 0, v[180:181]
	s_mov_b32 m0, s36
	s_nop 0
	global_load_lds_dwordx4 v[200:201], off
	v_lshl_add_u64 v[200:201], s[12:13], 0, v[170:171]
	s_add_i32 m0, s36, 0x2000
	s_nop 0
	global_load_lds_dwordx4 v[200:201], off
	v_lshl_add_u64 v[200:201], v[220:221], 0, s[96:97]
	s_mov_b32 m0, s50
	s_nop 0
	global_load_lds_dwordx4 v[200:201], off
	v_lshl_add_u64 v[200:201], v[222:223], 0, s[96:97]
	s_mov_b32 m0, s51
	s_nop 0
	global_load_lds_dwordx4 v[200:201], off
	s_waitcnt vmcnt(8)
	s_waitcnt lgkmcnt(0)
	s_barrier
	s_setprio 1
	s_waitcnt lgkmcnt(0)
	v_mfma_f32_16x16x32_bf16 v[62:65], v[66:69], v[162:165], v[62:65]
	v_mfma_f32_16x16x32_bf16 v[58:61], v[82:85], v[162:165], v[58:61]
	v_mfma_f32_16x16x32_bf16 v[46:49], v[66:69], v[188:191], v[46:49]
	v_mfma_f32_16x16x32_bf16 v[42:45], v[82:85], v[188:191], v[42:45]
	v_mfma_f32_16x16x32_bf16 v[30:33], v[66:69], v[196:199], v[30:33]
	v_mfma_f32_16x16x32_bf16 v[26:29], v[82:85], v[196:199], v[26:29]
	v_mfma_f32_16x16x32_bf16 v[14:17], v[66:69], v[210:213], v[14:17]
	v_mfma_f32_16x16x32_bf16 v[10:13], v[82:85], v[210:213], v[10:13]
	v_mfma_f32_16x16x32_bf16 v[62:65], v[70:73], v[166:169], v[62:65]
	v_mfma_f32_16x16x32_bf16 v[58:61], v[94:97], v[166:169], v[58:61]
	v_mfma_f32_16x16x32_bf16 v[46:49], v[70:73], v[192:195], v[46:49]
	v_mfma_f32_16x16x32_bf16 v[42:45], v[94:97], v[192:195], v[42:45]
	v_mfma_f32_16x16x32_bf16 v[30:33], v[70:73], v[206:209], v[30:33]
	v_mfma_f32_16x16x32_bf16 v[26:29], v[94:97], v[206:209], v[26:29]
	v_mfma_f32_16x16x32_bf16 v[14:17], v[70:73], v[214:217], v[14:17]
	v_mfma_f32_16x16x32_bf16 v[10:13], v[94:97], v[214:217], v[10:13]
	v_mfma_f32_16x16x32_bf16 v[54:57], v[106:109], v[162:165], v[54:57]
	v_mfma_f32_16x16x32_bf16 v[50:53], v[130:133], v[162:165], v[50:53]
	v_mfma_f32_16x16x32_bf16 v[38:41], v[106:109], v[188:191], v[38:41]
	v_mfma_f32_16x16x32_bf16 v[34:37], v[130:133], v[188:191], v[34:37]
	v_mfma_f32_16x16x32_bf16 v[22:25], v[106:109], v[196:199], v[22:25]
	v_mfma_f32_16x16x32_bf16 v[18:21], v[130:133], v[196:199], v[18:21]
	v_mfma_f32_16x16x32_bf16 v[6:9], v[106:109], v[210:213], v[6:9]
	v_mfma_f32_16x16x32_bf16 v[2:5], v[130:133], v[210:213], v[2:5]
	v_mfma_f32_16x16x32_bf16 v[54:57], v[118:121], v[166:169], v[54:57]
	v_mfma_f32_16x16x32_bf16 v[50:53], v[134:137], v[166:169], v[50:53]
	v_mfma_f32_16x16x32_bf16 v[38:41], v[118:121], v[192:195], v[38:41]
	v_mfma_f32_16x16x32_bf16 v[34:37], v[134:137], v[192:195], v[34:37]
	v_mfma_f32_16x16x32_bf16 v[22:25], v[118:121], v[206:209], v[22:25]
	v_mfma_f32_16x16x32_bf16 v[18:21], v[134:137], v[206:209], v[18:21]
	v_mfma_f32_16x16x32_bf16 v[6:9], v[118:121], v[214:217], v[6:9]
	v_mfma_f32_16x16x32_bf16 v[2:5], v[134:137], v[214:217], v[2:5]
	s_setprio 0
	s_barrier
	s_add_i32 s55, s55, 2
	s_add_u32 s10, s10, 0x100
	s_addc_u32 s11, s11, 0
	s_add_u32 s33, s33, 0x100
	s_addc_u32 s54, s54, 0
	s_cmp_gt_u32 s55, 13
	s_cbranch_scc0 .LBB0_633
	s_and_b64 vcc, exec, s[20:21]
	s_cbranch_vccz .LBB0_636
	s_barrier

; #define PG8_STAGE(bufoff, gbase, voff) do { _Pragma("unroll") for (int _i = 0; _i < 2; ++_i) \
;         __builtin_amdgcn_global_load_lds((const unsigned*)((const char*)(gbase) + (voff)[_i]), (PG8_LAS unsigned*)(lds + (bufoff) + ldsw + _i * 8192), 16, 0, 0); } while (0)
; #define PG8_LDA(dst, b, h) do { _Pragma("unroll") for (int m = 0; m < 4; ++m) _Pragma("unroll") for (int k = 0; k < 2; ++k) dst[m][k] = *(const PG8_LAS bf16x8*)(lds + PG8_SA(b, h) + aoff + m * 2048 + k * 1024); } while (0)
; #define PG8_MMA(ai, bj, At, Bt) do { __builtin_amdgcn_s_setprio(1); _Pragma("unroll") for (int m = 0; m < 4; ++m) _Pragma("unroll") for (int n = 0; n < 2; ++n) _Pragma("unroll") for (int k = 0; k < 2; ++k) \
;         acc[ai][bj][m][n] = __builtin_amdgcn_mfma_f32_16x16x32_bf16(Bt[n][k], At[m][k], acc[ai][bj][m][n], 0, 0, 0); __builtin_amdgcn_s_setprio(0); } while (0)
; #define PG8_WAIT_V(n) asm volatile("s_waitcnt vmcnt(" #n ")" ::: "memory")
; #define PG8_WAIT_L(n) asm volatile("s_waitcnt lgkmcnt(" #n ")" ::: "memory")
; #define PG8_BAR __builtin_amdgcn_s_barrier()
; #define PG8_SCHED __builtin_amdgcn_sched_barrier(0)
; template <class Epi, class Sched, bool ALIGN_EPI = false, bool SP2 = false>
; __device__ __forceinline__ void gemm_phase(PG8_LAS unsigned char* lds, const Gemm g, const Sched& S, const Epi& E) {
;     ...
;             PG8_WAIT_V(8); PG8_WAIT_L(0); PG8_BAR; PG8_MMA(0, 0, At, B0); PG8_MMA(0, 1, At, B1); PG8_BAR; PG8_SCHED;
;             PG8_LDA(At, 0, 1); PG8_STAGE(PG8_SB(0, 0), b2, voffB); PG8_STAGE(PG8_SB(0, 1), b2 + hstep, voffB); PG8_STAGE(PG8_SA(0, 0), a2, voffA);
;             PG8_WAIT_V(8); PG8_WAIT_L(0); PG8_BAR; PG8_MMA(1, 0, At, B0); PG8_MMA(1, 1, At, B1); PG8_BAR; PG8_SCHED;
.Levin_noz:
	s_waitcnt vmcnt(8)
	s_waitcnt lgkmcnt(0)
	s_barrier
	s_setprio 1
	s_waitcnt lgkmcnt(0)
	v_mfma_f32_16x16x32_bf16 v[126:129], v[150:153], v[188:191], v[126:129]
	v_mfma_f32_16x16x32_bf16 v[122:125], v[158:161], v[188:191], v[122:125]
	v_mfma_f32_16x16x32_bf16 v[114:117], v[150:153], v[196:199], v[114:117]
	v_mfma_f32_16x16x32_bf16 v[106:109], v[158:161], v[196:199], v[106:109]
	v_mfma_f32_16x16x32_bf16 v[98:101], v[150:153], v[204:207], v[98:101]
	v_mfma_f32_16x16x32_bf16 v[90:93], v[158:161], v[204:207], v[90:93]
	v_mfma_f32_16x16x32_bf16 v[82:85], v[150:153], v[212:215], v[82:85]
	v_mfma_f32_16x16x32_bf16 v[74:77], v[158:161], v[212:215], v[74:77]
	v_mfma_f32_16x16x32_bf16 v[126:129], v[154:157], v[192:195], v[126:129]
	v_mfma_f32_16x16x32_bf16 v[122:125], v[162:165], v[192:195], v[122:125]
	v_mfma_f32_16x16x32_bf16 v[114:117], v[154:157], v[200:203], v[114:117]
	v_mfma_f32_16x16x32_bf16 v[106:109], v[162:165], v[200:203], v[106:109]
	v_mfma_f32_16x16x32_bf16 v[98:101], v[154:157], v[208:211], v[98:101]
	v_mfma_f32_16x16x32_bf16 v[90:93], v[162:165], v[208:211], v[90:93]
	v_mfma_f32_16x16x32_bf16 v[82:85], v[154:157], v[216:219], v[82:85]
	v_mfma_f32_16x16x32_bf16 v[74:77], v[162:165], v[216:219], v[74:77]
	v_mfma_f32_16x16x32_bf16 v[118:121], v[166:169], v[188:191], v[118:121]
	v_mfma_f32_16x16x32_bf16 v[110:113], v[180:183], v[188:191], v[110:113]
	v_mfma_f32_16x16x32_bf16 v[102:105], v[166:169], v[196:199], v[102:105]
	v_mfma_f32_16x16x32_bf16 v[94:97], v[180:183], v[196:199], v[94:97]
	v_mfma_f32_16x16x32_bf16 v[86:89], v[166:169], v[204:207], v[86:89]
	v_mfma_f32_16x16x32_bf16 v[78:81], v[180:183], v[204:207], v[78:81]
	v_mfma_f32_16x16x32_bf16 v[70:73], v[166:169], v[212:215], v[70:73]
	v_mfma_f32_16x16x32_bf16 v[66:69], v[180:183], v[212:215], v[66:69]
	v_mfma_f32_16x16x32_bf16 v[118:121], v[170:173], v[192:195], v[118:121]
	v_mfma_f32_16x16x32_bf16 v[110:113], v[184:187], v[192:195], v[110:113]
	v_mfma_f32_16x16x32_bf16 v[102:105], v[170:173], v[200:203], v[102:105]
	v_mfma_f32_16x16x32_bf16 v[94:97], v[184:187], v[200:203], v[94:97]
	v_mfma_f32_16x16x32_bf16 v[86:89], v[170:173], v[208:211], v[86:89]
	v_mfma_f32_16x16x32_bf16 v[78:81], v[184:187], v[208:211], v[78:81]
	v_mfma_f32_16x16x32_bf16 v[70:73], v[170:173], v[216:219], v[70:73]
	v_mfma_f32_16x16x32_bf16 v[66:69], v[184:187], v[216:219], v[66:69]
	s_setprio 0
	s_barrier
	s_add_i32 s49, s49, s35
	v_lshl_add_u64 v[146:147], s[26:27], 0, v[134:135]
	s_mov_b32 m0, s49
	ds_read_b128 v[188:191], v149 offset:16384
	ds_read_b128 v[192:195], v149 offset:17408
	ds_read_b128 v[196:199], v149 offset:18432
	ds_read_b128 v[200:203], v149 offset:19456
	ds_read_b128 v[204:207], v149 offset:20480
	ds_read_b128 v[208:211], v149 offset:21504
	ds_read_b128 v[212:215], v149 offset:22528
	ds_read_b128 v[216:219], v149 offset:23552
	global_load_lds_dwordx4 v[146:147], off
	s_add_i32 m0, s49, 0x2000
	s_add_u32 s50, s26, 0x40000
	v_lshl_add_u64 v[220:221], s[26:27], 0, v[130:131]
	s_addc_u32 s51, s27, 0
	s_add_i32 s49, s52, s35
	global_load_lds_dwordx4 v[220:221], off
	v_lshl_add_u64 v[222:223], s[50:51], 0, v[134:135]
	s_mov_b32 m0, s49
	v_lshl_add_u64 v[228:229], s[28:29], 0, v[132:133]
	global_load_lds_dwordx4 v[222:223], off
	v_lshl_add_u64 v[222:223], s[50:51], 0, v[130:131]
	s_add_i32 m0, s49, 0x2000
	s_nop 0
	global_load_lds_dwordx4 v[222:223], off
	v_lshl_add_u64 v[222:223], s[28:29], 0, v[136:137]
	s_mov_b32 m0, s36
	s_nop 0
	global_load_lds_dwordx4 v[222:223], off
	s_mov_b32 m0, s37
	s_nop 0
	global_load_lds_dwordx4 v[228:229], off
	s_waitcnt vmcnt(8)
	s_waitcnt lgkmcnt(0)
	s_barrier
	s_setprio 1
	s_waitcnt lgkmcnt(0)
	v_mfma_f32_16x16x32_bf16 v[62:65], v[150:153], v[188:191], v[62:65]
	v_mfma_f32_16x16x32_bf16 v[58:61], v[158:161], v[188:191], v[58:61]
	v_mfma_f32_16x16x32_bf16 v[50:53], v[150:153], v[196:199], v[50:53]
	v_mfma_f32_16x16x32_bf16 v[42:45], v[158:161], v[196:199], v[42:45]
	v_mfma_f32_16x16x32_bf16 v[34:37], v[150:153], v[204:207], v[34:37]
	v_mfma_f32_16x16x32_bf16 v[26:29], v[158:161], v[204:207], v[26:29]
	v_mfma_f32_16x16x32_bf16 v[18:21], v[150:153], v[212:215], v[18:21]
	v_mfma_f32_16x16x32_bf16 v[10:13], v[158:161], v[212:215], v[10:13]
	v_mfma_f32_16x16x32_bf16 v[62:65], v[154:157], v[192:195], v[62:65]
	v_mfma_f32_16x16x32_bf16 v[58:61], v[162:165], v[192:195], v[58:61]
	v_mfma_f32_16x16x32_bf16 v[50:53], v[154:157], v[200:203], v[50:53]
	v_mfma_f32_16x16x32_bf16 v[42:45], v[162:165], v[200:203], v[42:45]
	v_mfma_f32_16x16x32_bf16 v[34:37], v[154:157], v[208:211], v[34:37]
	v_mfma_f32_16x16x32_bf16 v[26:29], v[162:165], v[208:211], v[26:29]
	v_mfma_f32_16x16x32_bf16 v[18:21], v[154:157], v[216:219], v[18:21]
	v_mfma_f32_16x16x32_bf16 v[10:13], v[162:165], v[216:219], v[10:13]
	v_mfma_f32_16x16x32_bf16 v[54:57], v[166:169], v[188:191], v[54:57]
	v_mfma_f32_16x16x32_bf16 v[46:49], v[180:183], v[188:191], v[46:49]
	v_mfma_f32_16x16x32_bf16 v[38:41], v[166:169], v[196:199], v[38:41]
	v_mfma_f32_16x16x32_bf16 v[30:33], v[180:183], v[196:199], v[30:33]
	v_mfma_f32_16x16x32_bf16 v[22:25], v[166:169], v[204:207], v[22:25]
	v_mfma_f32_16x16x32_bf16 v[14:17], v[180:183], v[204:207], v[14:17]
	v_mfma_f32_16x16x32_bf16 v[6:9], v[166:169], v[212:215], v[6:9]
	v_mfma_f32_16x16x32_bf16 v[2:5], v[180:183], v[212:215], v[2:5]
	v_mfma_f32_16x16x32_bf16 v[54:57], v[170:173], v[192:195], v[54:57]
	v_mfma_f32_16x16x32_bf16 v[46:49], v[184:187], v[192:195], v[46:49]
	v_mfma_f32_16x16x32_bf16 v[38:41], v[170:173], v[200:203], v[38:41]
	v_mfma_f32_16x16x32_bf16 v[30:33], v[184:187], v[200:203], v[30:33]
	v_mfma_f32_16x16x32_bf16 v[22:25], v[170:173], v[208:211], v[22:25]
	v_mfma_f32_16x16x32_bf16 v[14:17], v[184:187], v[208:211], v[14:17]
	v_mfma_f32_16x16x32_bf16 v[6:9], v[170:173], v[216:219], v[6:9]
	v_mfma_f32_16x16x32_bf16 v[2:5], v[184:187], v[216:219], v[2:5]
	s_setprio 0
	s_barrier
; #define PG8_STAGE(bufoff, gbase, voff) do { _Pragma("unroll") for (int _i = 0; _i < 2; ++_i) \
;         __builtin_amdgcn_global_load_lds((const unsigned*)((const char*)(gbase) + (voff)[_i]), (PG8_LAS unsigned*)(lds + (bufoff) + ldsw + _i * 8192), 16, 0, 0); } while (0)
; #define PG8_LDA(dst, b, h) do { _Pragma("unroll") for (int m = 0; m < 4; ++m) _Pragma("unroll") for (int k = 0; k < 2; ++k) dst[m][k] = *(const PG8_LAS bf16x8*)(lds + PG8_SA(b, h) + aoff + m * 2048 + k * 1024); } while (0)
; #define PG8_LDB(dst, b, h) do { _Pragma("unroll") for (int n = 0; n < 2; ++n) _Pragma("unroll") for (int k = 0; k < 2; ++k) dst[n][k] = *(const PG8_LAS bf16x8*)(lds + PG8_SB(b, h) + boff + n * 2048 + k * 1024); } while (0)
; #define PG8_MMA(ai, bj, At, Bt) do { __builtin_amdgcn_s_setprio(1); _Pragma("unroll") for (int m = 0; m < 4; ++m) _Pragma("unroll") for (int n = 0; n < 2; ++n) _Pragma("unroll") for (int k = 0; k < 2; ++k) \
;         acc[ai][bj][m][n] = __builtin_amdgcn_mfma_f32_16x16x32_bf16(Bt[n][k], At[m][k], acc[ai][bj][m][n], 0, 0, 0); __builtin_amdgcn_s_setprio(0); } while (0)
; #define PG8_WAIT_V(n) asm volatile("s_waitcnt vmcnt(" #n ")" ::: "memory")
; #define PG8_WAIT_L(n) asm volatile("s_waitcnt lgkmcnt(" #n ")" ::: "memory")
; #define PG8_BAR __builtin_amdgcn_s_barrier()
; #define PG8_SCHED __builtin_amdgcn_sched_barrier(0)
; template <class Epi, class Sched, bool ALIGN_EPI = false, bool SP2 = false>
; __device__ __forceinline__ void gemm_phase(PG8_LAS unsigned char* lds, const Gemm g, const Sched& S, const Epi& E) {
;     ...
;             PG8_LDB(B0, 1, 0); PG8_LDB(B1, 1, 1); PG8_SCHED; PG8_LDA(At, 1, 0); PG8_STAGE(PG8_SA(0, 1), a2 + hstep, voffA);
;             PG8_WAIT_V(8); PG8_WAIT_L(0); PG8_BAR; PG8_MMA(0, 0, At, B0); PG8_MMA(0, 1, At, B1); PG8_BAR; PG8_SCHED;
	s_add_i32 s49, 0, 0x18000
	v_add_u32_e32 v142, s49, v145
	s_add_i32 s50, 0, 0x1c000
	ds_read_b128 v[150:153], v142
	ds_read_b128 v[154:157], v142 offset:1024
	ds_read_b128 v[158:161], v142 offset:2048
	ds_read_b128 v[162:165], v142 offset:3072
	v_add_u32_e32 v142, s50, v145
	ds_read_b128 v[166:169], v142
	ds_read_b128 v[170:173], v142 offset:1024
	ds_read_b128 v[180:183], v142 offset:2048
	ds_read_b128 v[184:187], v142 offset:3072
	s_add_u32 s28, s28, 0x40000
	s_addc_u32 s29, s29, 0
	s_mov_b32 m0, s38
	v_lshl_add_u64 v[230:231], s[28:29], 0, v[136:137]
	ds_read_b128 v[188:191], v149 offset:32768
	ds_read_b128 v[192:195], v149 offset:33792
	ds_read_b128 v[196:199], v149 offset:34816
	ds_read_b128 v[200:203], v149 offset:35840
	ds_read_b128 v[204:207], v149 offset:36864
	ds_read_b128 v[208:211], v149 offset:37888
	ds_read_b128 v[212:215], v149 offset:38912
	ds_read_b128 v[216:219], v149 offset:39936
	global_load_lds_dwordx4 v[230:231], off
	v_lshl_add_u64 v[230:231], s[28:29], 0, v[132:133]
	s_mov_b32 m0, s39
	s_nop 0
	global_load_lds_dwordx4 v[230:231], off
	s_waitcnt vmcnt(8)
	s_waitcnt lgkmcnt(0)
	s_barrier
	s_setprio 1
	s_waitcnt lgkmcnt(0)
	v_mfma_f32_16x16x32_bf16 v[126:129], v[150:153], v[188:191], v[126:129]
	v_mfma_f32_16x16x32_bf16 v[122:125], v[158:161], v[188:191], v[122:125]
	v_mfma_f32_16x16x32_bf16 v[114:117], v[150:153], v[196:199], v[114:117]
	v_mfma_f32_16x16x32_bf16 v[106:109], v[158:161], v[196:199], v[106:109]
	v_mfma_f32_16x16x32_bf16 v[98:101], v[150:153], v[204:207], v[98:101]
	v_mfma_f32_16x16x32_bf16 v[90:93], v[158:161], v[204:207], v[90:93]
	v_mfma_f32_16x16x32_bf16 v[82:85], v[150:153], v[212:215], v[82:85]
	v_mfma_f32_16x16x32_bf16 v[74:77], v[158:161], v[212:215], v[74:77]
	v_mfma_f32_16x16x32_bf16 v[126:129], v[154:157], v[192:195], v[126:129]
	v_mfma_f32_16x16x32_bf16 v[122:125], v[162:165], v[192:195], v[122:125]
	v_mfma_f32_16x16x32_bf16 v[114:117], v[154:157], v[200:203], v[114:117]
	v_mfma_f32_16x16x32_bf16 v[106:109], v[162:165], v[200:203], v[106:109]
	v_mfma_f32_16x16x32_bf16 v[98:101], v[154:157], v[208:211], v[98:101]
	v_mfma_f32_16x16x32_bf16 v[90:93], v[162:165], v[208:211], v[90:93]
	v_mfma_f32_16x16x32_bf16 v[82:85], v[154:157], v[216:219], v[82:85]
	v_mfma_f32_16x16x32_bf16 v[74:77], v[162:165], v[216:219], v[74:77]
	v_mfma_f32_16x16x32_bf16 v[118:121], v[166:169], v[188:191], v[118:121]
	v_mfma_f32_16x16x32_bf16 v[110:113], v[180:183], v[188:191], v[110:113]
	v_mfma_f32_16x16x32_bf16 v[102:105], v[166:169], v[196:199], v[102:105]
	v_mfma_f32_16x16x32_bf16 v[94:97], v[180:183], v[196:199], v[94:97]
	v_mfma_f32_16x16x32_bf16 v[86:89], v[166:169], v[204:207], v[86:89]
	v_mfma_f32_16x16x32_bf16 v[78:81], v[180:183], v[204:207], v[78:81]
	v_mfma_f32_16x16x32_bf16 v[70:73], v[166:169], v[212:215], v[70:73]
	v_mfma_f32_16x16x32_bf16 v[66:69], v[180:183], v[212:215], v[66:69]
	v_mfma_f32_16x16x32_bf16 v[118:121], v[170:173], v[192:195], v[118:121]
	v_mfma_f32_16x16x32_bf16 v[110:113], v[184:187], v[192:195], v[110:113]
	v_mfma_f32_16x16x32_bf16 v[102:105], v[170:173], v[200:203], v[102:105]
	v_mfma_f32_16x16x32_bf16 v[94:97], v[184:187], v[200:203], v[94:97]
	v_mfma_f32_16x16x32_bf16 v[86:89], v[170:173], v[208:211], v[86:89]
	v_mfma_f32_16x16x32_bf16 v[78:81], v[184:187], v[208:211], v[78:81]
	v_mfma_f32_16x16x32_bf16 v[70:73], v[170:173], v[216:219], v[70:73]
	v_mfma_f32_16x16x32_bf16 v[66:69], v[184:187], v[216:219], v[66:69]
	s_setprio 0
	s_barrier
; #define PG8_STAGE(bufoff, gbase, voff) do { _Pragma("unroll") for (int _i = 0; _i < 2; ++_i) \
;         __builtin_amdgcn_global_load_lds((const unsigned*)((const char*)(gbase) + (voff)[_i]), (PG8_LAS unsigned*)(lds + (bufoff) + ldsw + _i * 8192), 16, 0, 0); } while (0)
; #define PG8_LDA(dst, b, h) do { _Pragma("unroll") for (int m = 0; m < 4; ++m) _Pragma("unroll") for (int k = 0; k < 2; ++k) dst[m][k] = *(const PG8_LAS bf16x8*)(lds + PG8_SA(b, h) + aoff + m * 2048 + k * 1024); } while (0)
; #define PG8_MMA(ai, bj, At, Bt) do { __builtin_amdgcn_s_setprio(1); _Pragma("unroll") for (int m = 0; m < 4; ++m) _Pragma("unroll") for (int n = 0; n < 2; ++n) _Pragma("unroll") for (int k = 0; k < 2; ++k) \
;         acc[ai][bj][m][n] = __builtin_amdgcn_mfma_f32_16x16x32_bf16(Bt[n][k], At[m][k], acc[ai][bj][m][n], 0, 0, 0); __builtin_amdgcn_s_setprio(0); } while (0)
; #define PG8_WAIT_V(n) asm volatile("s_waitcnt vmcnt(" #n ")" ::: "memory")
; #define PG8_WAIT_L(n) asm volatile("s_waitcnt lgkmcnt(" #n ")" ::: "memory")
; #define PG8_BAR __builtin_amdgcn_s_barrier()
; #define PG8_SCHED __builtin_amdgcn_sched_barrier(0)
; template <class Epi, class Sched, bool ALIGN_EPI = false, bool SP2 = false>
; __device__ __forceinline__ void gemm_phase(PG8_LAS unsigned char* lds, const Gemm g, const Sched& S, const Epi& E) {
;     ...
;         for (int t = 0; t < nt; t += 2) {
;     ...
;             PG8_LDA(At, 1, 1); PG8_STAGE(PG8_SB(1, 0), b3, voffB); PG8_STAGE(PG8_SB(1, 1), b3 + hstep, voffB); PG8_STAGE(PG8_SA(1, 0), a3, voffA);
;             PG8_WAIT_V(8); PG8_WAIT_L(0); PG8_BAR; PG8_MMA(1, 0, At, B0); PG8_MMA(1, 1, At, B1); PG8_BAR; PG8_SCHED;
	s_add_i32 s28, s49, s35
	v_lshl_add_u64 v[146:147], v[146:147], 0, s[96:97]
	s_mov_b32 m0, s28
	ds_read_b128 v[188:191], v149 offset:49152
	ds_read_b128 v[192:195], v149 offset:50176
	ds_read_b128 v[196:199], v149 offset:51200
	ds_read_b128 v[200:203], v149 offset:52224
	ds_read_b128 v[204:207], v149 offset:53248
	ds_read_b128 v[208:211], v149 offset:54272
	ds_read_b128 v[212:215], v149 offset:55296
	ds_read_b128 v[216:219], v149 offset:56320
	global_load_lds_dwordx4 v[146:147], off
	s_add_i32 m0, s28, 0x2000
	s_add_u32 s26, s26, 0x40080
	v_lshl_add_u64 v[146:147], v[220:221], 0, s[96:97]
	s_addc_u32 s27, s27, 0
	s_add_i32 s28, s50, s35
	global_load_lds_dwordx4 v[146:147], off
	v_lshl_add_u64 v[146:147], s[26:27], 0, v[134:135]
	s_mov_b32 m0, s28
	s_nop 0
	global_load_lds_dwordx4 v[146:147], off
	v_lshl_add_u64 v[146:147], s[26:27], 0, v[130:131]
	s_add_i32 m0, s28, 0x2000
	s_nop 0
	global_load_lds_dwordx4 v[146:147], off
	v_lshl_add_u64 v[146:147], v[222:223], 0, s[96:97]
	s_mov_b32 m0, s42
	s_nop 0
	global_load_lds_dwordx4 v[146:147], off
	v_lshl_add_u64 v[146:147], v[228:229], 0, s[96:97]
	s_mov_b32 m0, s43
	s_nop 0
	global_load_lds_dwordx4 v[146:147], off
	s_waitcnt vmcnt(8)
	s_waitcnt lgkmcnt(0)
	s_barrier
	s_setprio 1
	s_waitcnt lgkmcnt(0)
	v_mfma_f32_16x16x32_bf16 v[62:65], v[150:153], v[188:191], v[62:65]
	v_mfma_f32_16x16x32_bf16 v[58:61], v[158:161], v[188:191], v[58:61]
	v_mfma_f32_16x16x32_bf16 v[50:53], v[150:153], v[196:199], v[50:53]
	v_mfma_f32_16x16x32_bf16 v[42:45], v[158:161], v[196:199], v[42:45]
	v_mfma_f32_16x16x32_bf16 v[34:37], v[150:153], v[204:207], v[34:37]
	v_mfma_f32_16x16x32_bf16 v[26:29], v[158:161], v[204:207], v[26:29]
	v_mfma_f32_16x16x32_bf16 v[18:21], v[150:153], v[212:215], v[18:21]
	v_mfma_f32_16x16x32_bf16 v[10:13], v[158:161], v[212:215], v[10:13]
	v_mfma_f32_16x16x32_bf16 v[62:65], v[154:157], v[192:195], v[62:65]
	v_mfma_f32_16x16x32_bf16 v[58:61], v[162:165], v[192:195], v[58:61]
	v_mfma_f32_16x16x32_bf16 v[50:53], v[154:157], v[200:203], v[50:53]
	v_mfma_f32_16x16x32_bf16 v[42:45], v[162:165], v[200:203], v[42:45]
	v_mfma_f32_16x16x32_bf16 v[34:37], v[154:157], v[208:211], v[34:37]
	v_mfma_f32_16x16x32_bf16 v[26:29], v[162:165], v[208:211], v[26:29]
	v_mfma_f32_16x16x32_bf16 v[18:21], v[154:157], v[216:219], v[18:21]
	v_mfma_f32_16x16x32_bf16 v[10:13], v[162:165], v[216:219], v[10:13]
	v_mfma_f32_16x16x32_bf16 v[54:57], v[166:169], v[188:191], v[54:57]
	v_mfma_f32_16x16x32_bf16 v[46:49], v[180:183], v[188:191], v[46:49]
	v_mfma_f32_16x16x32_bf16 v[38:41], v[166:169], v[196:199], v[38:41]
	v_mfma_f32_16x16x32_bf16 v[30:33], v[180:183], v[196:199], v[30:33]
	v_mfma_f32_16x16x32_bf16 v[22:25], v[166:169], v[204:207], v[22:25]
	v_mfma_f32_16x16x32_bf16 v[14:17], v[180:183], v[204:207], v[14:17]
	v_mfma_f32_16x16x32_bf16 v[6:9], v[166:169], v[212:215], v[6:9]
	v_mfma_f32_16x16x32_bf16 v[2:5], v[180:183], v[212:215], v[2:5]
	v_mfma_f32_16x16x32_bf16 v[54:57], v[170:173], v[192:195], v[54:57]
	v_mfma_f32_16x16x32_bf16 v[46:49], v[184:187], v[192:195], v[46:49]
	v_mfma_f32_16x16x32_bf16 v[38:41], v[170:173], v[200:203], v[38:41]
	v_mfma_f32_16x16x32_bf16 v[30:33], v[184:187], v[200:203], v[30:33]
	v_mfma_f32_16x16x32_bf16 v[22:25], v[170:173], v[208:211], v[22:25]
	v_mfma_f32_16x16x32_bf16 v[14:17], v[184:187], v[208:211], v[14:17]
	v_mfma_f32_16x16x32_bf16 v[6:9], v[170:173], v[216:219], v[6:9]
	v_mfma_f32_16x16x32_bf16 v[2:5], v[184:187], v[216:219], v[2:5]
	s_setprio 0
	s_barrier
	s_add_i32 s48, s48, 2
	s_add_u32 s24, s24, 0x100
	s_addc_u32 s25, s25, 0
	s_add_u32 s46, s46, 0x100
	s_addc_u32 s47, s47, 0
	s_cmp_gt_u32 s48, 13
	s_cbranch_scc0 .LBB0_812
	s_and_b64 vcc, exec, s[14:15]
	s_cbranch_vccz .LBB0_815
	s_barrier

; #define PG8_STAGE(bufoff, gbase, voff) do { _Pragma("unroll") for (int _i = 0; _i < 2; ++_i) \
;         __builtin_amdgcn_global_load_lds((const unsigned*)((const char*)(gbase) + (voff)[_i]), (PG8_LAS unsigned*)(lds + (bufoff) + ldsw + _i * 8192), 16, 0, 0); } while (0)
; #define PG8_LDA(dst, b, h) do { _Pragma("unroll") for (int m = 0; m < 4; ++m) _Pragma("unroll") for (int k = 0; k < 2; ++k) dst[m][k] = *(const PG8_LAS bf16x8*)(lds + PG8_SA(b, h) + aoff + m * 2048 + k * 1024); } while (0)
; #define PG8_MMA(ai, bj, At, Bt) do { __builtin_amdgcn_s_setprio(1); _Pragma("unroll") for (int m = 0; m < 4; ++m) _Pragma("unroll") for (int n = 0; n < 2; ++n) _Pragma("unroll") for (int k = 0; k < 2; ++k) \
;         acc[ai][bj][m][n] = __builtin_amdgcn_mfma_f32_16x16x32_bf16(Bt[n][k], At[m][k], acc[ai][bj][m][n], 0, 0, 0); __builtin_amdgcn_s_setprio(0); } while (0)
; #define PG8_WAIT_V(n) asm volatile("s_waitcnt vmcnt(" #n ")" ::: "memory")
; #define PG8_WAIT_L(n) asm volatile("s_waitcnt lgkmcnt(" #n ")" ::: "memory")
; #define PG8_BAR __builtin_amdgcn_s_barrier()
; #define PG8_SCHED __builtin_amdgcn_sched_barrier(0)
; template <class Epi, class Sched, bool ALIGN_EPI = false, bool SP2 = false>
; __device__ __forceinline__ void gemm_phase(PG8_LAS unsigned char* lds, const Gemm g, const Sched& S, const Epi& E) {
;     ...
;             PG8_WAIT_V(8); PG8_WAIT_L(0); PG8_BAR; PG8_MMA(0, 0, At, B0); PG8_MMA(0, 1, At, B1); PG8_BAR; PG8_SCHED;
;             PG8_LDA(At, 0, 1); PG8_STAGE(PG8_SB(0, 0), b2, voffB); PG8_STAGE(PG8_SB(0, 1), b2 + hstep, voffB); PG8_STAGE(PG8_SA(0, 0), a2, voffA);
;             PG8_WAIT_V(8); PG8_WAIT_L(0); PG8_BAR; PG8_MMA(1, 0, At, B0); PG8_MMA(1, 1, At, B1); PG8_BAR; PG8_SCHED;
.Levout_noz:
	s_waitcnt vmcnt(8)
	s_waitcnt lgkmcnt(0)
	s_barrier
	s_setprio 1
	s_waitcnt lgkmcnt(0)
	v_mfma_f32_16x16x32_bf16 v[158:161], v[66:69], v[162:165], v[158:161]
	v_mfma_f32_16x16x32_bf16 v[154:157], v[82:85], v[162:165], v[154:157]
	v_mfma_f32_16x16x32_bf16 v[142:145], v[66:69], v[188:191], v[142:145]
	v_mfma_f32_16x16x32_bf16 v[138:141], v[82:85], v[188:191], v[138:141]
	v_mfma_f32_16x16x32_bf16 v[114:117], v[66:69], v[196:199], v[114:117]
	v_mfma_f32_16x16x32_bf16 v[110:113], v[82:85], v[196:199], v[110:113]
	v_mfma_f32_16x16x32_bf16 v[90:93], v[66:69], v[210:213], v[90:93]
	v_mfma_f32_16x16x32_bf16 v[86:89], v[82:85], v[210:213], v[86:89]
	v_mfma_f32_16x16x32_bf16 v[158:161], v[70:73], v[166:169], v[158:161]
	v_mfma_f32_16x16x32_bf16 v[154:157], v[94:97], v[166:169], v[154:157]
	v_mfma_f32_16x16x32_bf16 v[142:145], v[70:73], v[192:195], v[142:145]
	v_mfma_f32_16x16x32_bf16 v[138:141], v[94:97], v[192:195], v[138:141]
	v_mfma_f32_16x16x32_bf16 v[114:117], v[70:73], v[206:209], v[114:117]
	v_mfma_f32_16x16x32_bf16 v[110:113], v[94:97], v[206:209], v[110:113]
	v_mfma_f32_16x16x32_bf16 v[90:93], v[70:73], v[214:217], v[90:93]
	v_mfma_f32_16x16x32_bf16 v[86:89], v[94:97], v[214:217], v[86:89]
	v_mfma_f32_16x16x32_bf16 v[150:153], v[106:109], v[162:165], v[150:153]
	v_mfma_f32_16x16x32_bf16 v[146:149], v[130:133], v[162:165], v[146:149]
	v_mfma_f32_16x16x32_bf16 v[126:129], v[106:109], v[188:191], v[126:129]
	v_mfma_f32_16x16x32_bf16 v[122:125], v[130:133], v[188:191], v[122:125]
	v_mfma_f32_16x16x32_bf16 v[102:105], v[106:109], v[196:199], v[102:105]
	v_mfma_f32_16x16x32_bf16 v[98:101], v[130:133], v[196:199], v[98:101]
	v_mfma_f32_16x16x32_bf16 v[78:81], v[106:109], v[210:213], v[78:81]
	v_mfma_f32_16x16x32_bf16 v[74:77], v[130:133], v[210:213], v[74:77]
	v_mfma_f32_16x16x32_bf16 v[150:153], v[118:121], v[166:169], v[150:153]
	v_mfma_f32_16x16x32_bf16 v[146:149], v[134:137], v[166:169], v[146:149]
	v_mfma_f32_16x16x32_bf16 v[126:129], v[118:121], v[192:195], v[126:129]
	v_mfma_f32_16x16x32_bf16 v[122:125], v[134:137], v[192:195], v[122:125]
	v_mfma_f32_16x16x32_bf16 v[102:105], v[118:121], v[206:209], v[102:105]
	v_mfma_f32_16x16x32_bf16 v[98:101], v[134:137], v[206:209], v[98:101]
	v_mfma_f32_16x16x32_bf16 v[78:81], v[118:121], v[214:217], v[78:81]
	v_mfma_f32_16x16x32_bf16 v[74:77], v[134:137], v[214:217], v[74:77]
	s_setprio 0
	s_barrier
	s_add_i32 s56, s56, s42
	v_lshl_add_u64 v[200:201], s[10:11], 0, v[180:181]
	s_mov_b32 m0, s56
	ds_read_b128 v[162:165], v204 offset:16384
	ds_read_b128 v[166:169], v204 offset:17408
	ds_read_b128 v[188:191], v204 offset:18432
	ds_read_b128 v[192:195], v204 offset:19456
	ds_read_b128 v[196:199], v204 offset:20480
	ds_read_b128 v[206:209], v204 offset:21504
	ds_read_b128 v[210:213], v204 offset:22528
	ds_read_b128 v[214:217], v204 offset:23552
	global_load_lds_dwordx4 v[200:201], off
	s_add_i32 m0, s56, 0x2000
	s_add_u32 s56, s10, 0x40000
	v_lshl_add_u64 v[218:219], s[10:11], 0, v[170:171]
	s_addc_u32 s57, s11, 0
	s_add_i32 s58, s58, s42
	global_load_lds_dwordx4 v[218:219], off
	v_lshl_add_u64 v[220:221], s[56:57], 0, v[180:181]
	s_mov_b32 m0, s58
	v_lshl_add_u64 v[222:223], s[36:37], 0, v[172:173]
	global_load_lds_dwordx4 v[220:221], off
	v_lshl_add_u64 v[220:221], s[56:57], 0, v[170:171]
	s_add_i32 m0, s58, 0x2000
	s_nop 0
	global_load_lds_dwordx4 v[220:221], off
	v_lshl_add_u64 v[220:221], s[36:37], 0, v[182:183]
	s_mov_b32 m0, s43
	s_nop 0
	global_load_lds_dwordx4 v[220:221], off
	s_mov_b32 m0, s44
	s_nop 0
	global_load_lds_dwordx4 v[222:223], off
	s_waitcnt vmcnt(8)
	s_waitcnt lgkmcnt(0)
	s_barrier
	s_setprio 1
	s_waitcnt lgkmcnt(0)
	v_mfma_f32_16x16x32_bf16 v[62:65], v[66:69], v[162:165], v[62:65]
	v_mfma_f32_16x16x32_bf16 v[58:61], v[82:85], v[162:165], v[58:61]
	v_mfma_f32_16x16x32_bf16 v[46:49], v[66:69], v[188:191], v[46:49]
	v_mfma_f32_16x16x32_bf16 v[42:45], v[82:85], v[188:191], v[42:45]
	v_mfma_f32_16x16x32_bf16 v[30:33], v[66:69], v[196:199], v[30:33]
	v_mfma_f32_16x16x32_bf16 v[26:29], v[82:85], v[196:199], v[26:29]
	v_mfma_f32_16x16x32_bf16 v[14:17], v[66:69], v[210:213], v[14:17]
	v_mfma_f32_16x16x32_bf16 v[10:13], v[82:85], v[210:213], v[10:13]
	v_mfma_f32_16x16x32_bf16 v[62:65], v[70:73], v[166:169], v[62:65]
	v_mfma_f32_16x16x32_bf16 v[58:61], v[94:97], v[166:169], v[58:61]
	v_mfma_f32_16x16x32_bf16 v[46:49], v[70:73], v[192:195], v[46:49]
	v_mfma_f32_16x16x32_bf16 v[42:45], v[94:97], v[192:195], v[42:45]
	v_mfma_f32_16x16x32_bf16 v[30:33], v[70:73], v[206:209], v[30:33]
	v_mfma_f32_16x16x32_bf16 v[26:29], v[94:97], v[206:209], v[26:29]
	v_mfma_f32_16x16x32_bf16 v[14:17], v[70:73], v[214:217], v[14:17]
	v_mfma_f32_16x16x32_bf16 v[10:13], v[94:97], v[214:217], v[10:13]
	v_mfma_f32_16x16x32_bf16 v[54:57], v[106:109], v[162:165], v[54:57]
	v_mfma_f32_16x16x32_bf16 v[50:53], v[130:133], v[162:165], v[50:53]
	v_mfma_f32_16x16x32_bf16 v[38:41], v[106:109], v[188:191], v[38:41]
	v_mfma_f32_16x16x32_bf16 v[34:37], v[130:133], v[188:191], v[34:37]
	v_mfma_f32_16x16x32_bf16 v[22:25], v[106:109], v[196:199], v[22:25]
	v_mfma_f32_16x16x32_bf16 v[18:21], v[130:133], v[196:199], v[18:21]
	v_mfma_f32_16x16x32_bf16 v[6:9], v[106:109], v[210:213], v[6:9]
	v_mfma_f32_16x16x32_bf16 v[2:5], v[130:133], v[210:213], v[2:5]
	v_mfma_f32_16x16x32_bf16 v[54:57], v[118:121], v[166:169], v[54:57]
	v_mfma_f32_16x16x32_bf16 v[50:53], v[134:137], v[166:169], v[50:53]
	v_mfma_f32_16x16x32_bf16 v[38:41], v[118:121], v[192:195], v[38:41]
	v_mfma_f32_16x16x32_bf16 v[34:37], v[134:137], v[192:195], v[34:37]
	v_mfma_f32_16x16x32_bf16 v[22:25], v[118:121], v[206:209], v[22:25]
	v_mfma_f32_16x16x32_bf16 v[18:21], v[134:137], v[206:209], v[18:21]
	v_mfma_f32_16x16x32_bf16 v[6:9], v[118:121], v[214:217], v[6:9]
	v_mfma_f32_16x16x32_bf16 v[2:5], v[134:137], v[214:217], v[2:5]
	s_setprio 0
	s_barrier
; #define PG8_STAGE(bufoff, gbase, voff) do { _Pragma("unroll") for (int _i = 0; _i < 2; ++_i) \
;         __builtin_amdgcn_global_load_lds((const unsigned*)((const char*)(gbase) + (voff)[_i]), (PG8_LAS unsigned*)(lds + (bufoff) + ldsw + _i * 8192), 16, 0, 0); } while (0)
; #define PG8_LDA(dst, b, h) do { _Pragma("unroll") for (int m = 0; m < 4; ++m) _Pragma("unroll") for (int k = 0; k < 2; ++k) dst[m][k] = *(const PG8_LAS bf16x8*)(lds + PG8_SA(b, h) + aoff + m * 2048 + k * 1024); } while (0)
; #define PG8_LDB(dst, b, h) do { _Pragma("unroll") for (int n = 0; n < 2; ++n) _Pragma("unroll") for (int k = 0; k < 2; ++k) dst[n][k] = *(const PG8_LAS bf16x8*)(lds + PG8_SB(b, h) + boff + n * 2048 + k * 1024); } while (0)
; #define PG8_MMA(ai, bj, At, Bt) do { __builtin_amdgcn_s_setprio(1); _Pragma("unroll") for (int m = 0; m < 4; ++m) _Pragma("unroll") for (int n = 0; n < 2; ++n) _Pragma("unroll") for (int k = 0; k < 2; ++k) \
;         acc[ai][bj][m][n] = __builtin_amdgcn_mfma_f32_16x16x32_bf16(Bt[n][k], At[m][k], acc[ai][bj][m][n], 0, 0, 0); __builtin_amdgcn_s_setprio(0); } while (0)
; #define PG8_WAIT_V(n) asm volatile("s_waitcnt vmcnt(" #n ")" ::: "memory")
; #define PG8_WAIT_L(n) asm volatile("s_waitcnt lgkmcnt(" #n ")" ::: "memory")
; #define PG8_BAR __builtin_amdgcn_s_barrier()
; #define PG8_SCHED __builtin_amdgcn_sched_barrier(0)
; template <class Epi, class Sched, bool ALIGN_EPI = false, bool SP2 = false>
; __device__ __forceinline__ void gemm_phase(PG8_LAS unsigned char* lds, const Gemm g, const Sched& S, const Epi& E) {
;     ...
;             PG8_LDB(B0, 1, 0); PG8_LDB(B1, 1, 1); PG8_SCHED; PG8_LDA(At, 1, 0); PG8_STAGE(PG8_SA(0, 1), a2 + hstep, voffA);
;             PG8_WAIT_V(8); PG8_WAIT_L(0); PG8_BAR; PG8_MMA(0, 0, At, B0); PG8_MMA(0, 1, At, B1); PG8_BAR; PG8_SCHED;
	s_add_i32 s56, 0, 0x18000
	s_add_i32 s57, 0, 0x1c000
	v_add_u32_e32 v94, s56, v203
	v_add_u32_e32 v134, s57, v203
	ds_read_b128 v[66:69], v94
	ds_read_b128 v[70:73], v94 offset:1024
	ds_read_b128 v[82:85], v94 offset:2048
	ds_read_b128 v[94:97], v94 offset:3072
	ds_read_b128 v[106:109], v134
	ds_read_b128 v[118:121], v134 offset:1024
	ds_read_b128 v[130:133], v134 offset:2048
	ds_read_b128 v[134:137], v134 offset:3072
	s_add_u32 s36, s36, 0x40000
	s_addc_u32 s37, s37, 0
	s_mov_b32 m0, s45
	v_lshl_add_u64 v[228:229], s[36:37], 0, v[182:183]
	ds_read_b128 v[162:165], v204 offset:32768
	ds_read_b128 v[166:169], v204 offset:33792
	ds_read_b128 v[188:191], v204 offset:34816
	ds_read_b128 v[192:195], v204 offset:35840
	ds_read_b128 v[196:199], v204 offset:36864
	ds_read_b128 v[206:209], v204 offset:37888
	ds_read_b128 v[210:213], v204 offset:38912
	ds_read_b128 v[214:217], v204 offset:39936
	global_load_lds_dwordx4 v[228:229], off
	v_lshl_add_u64 v[228:229], s[36:37], 0, v[172:173]
	s_mov_b32 m0, s46
	s_nop 0
	global_load_lds_dwordx4 v[228:229], off
	s_waitcnt vmcnt(8)
	s_waitcnt lgkmcnt(0)
	s_barrier
	s_setprio 1
	s_waitcnt lgkmcnt(0)
	v_mfma_f32_16x16x32_bf16 v[158:161], v[66:69], v[162:165], v[158:161]
	v_mfma_f32_16x16x32_bf16 v[154:157], v[82:85], v[162:165], v[154:157]
	v_mfma_f32_16x16x32_bf16 v[142:145], v[66:69], v[188:191], v[142:145]
	v_mfma_f32_16x16x32_bf16 v[138:141], v[82:85], v[188:191], v[138:141]
	v_mfma_f32_16x16x32_bf16 v[114:117], v[66:69], v[196:199], v[114:117]
	v_mfma_f32_16x16x32_bf16 v[110:113], v[82:85], v[196:199], v[110:113]
	v_mfma_f32_16x16x32_bf16 v[90:93], v[66:69], v[210:213], v[90:93]
	v_mfma_f32_16x16x32_bf16 v[86:89], v[82:85], v[210:213], v[86:89]
	v_mfma_f32_16x16x32_bf16 v[158:161], v[70:73], v[166:169], v[158:161]
	v_mfma_f32_16x16x32_bf16 v[154:157], v[94:97], v[166:169], v[154:157]
	v_mfma_f32_16x16x32_bf16 v[142:145], v[70:73], v[192:195], v[142:145]
	v_mfma_f32_16x16x32_bf16 v[138:141], v[94:97], v[192:195], v[138:141]
	v_mfma_f32_16x16x32_bf16 v[114:117], v[70:73], v[206:209], v[114:117]
	v_mfma_f32_16x16x32_bf16 v[110:113], v[94:97], v[206:209], v[110:113]
	v_mfma_f32_16x16x32_bf16 v[90:93], v[70:73], v[214:217], v[90:93]
	v_mfma_f32_16x16x32_bf16 v[86:89], v[94:97], v[214:217], v[86:89]
	v_mfma_f32_16x16x32_bf16 v[150:153], v[106:109], v[162:165], v[150:153]
	v_mfma_f32_16x16x32_bf16 v[146:149], v[130:133], v[162:165], v[146:149]
	v_mfma_f32_16x16x32_bf16 v[126:129], v[106:109], v[188:191], v[126:129]
	v_mfma_f32_16x16x32_bf16 v[122:125], v[130:133], v[188:191], v[122:125]
	v_mfma_f32_16x16x32_bf16 v[102:105], v[106:109], v[196:199], v[102:105]
	v_mfma_f32_16x16x32_bf16 v[98:101], v[130:133], v[196:199], v[98:101]
	v_mfma_f32_16x16x32_bf16 v[78:81], v[106:109], v[210:213], v[78:81]
	v_mfma_f32_16x16x32_bf16 v[74:77], v[130:133], v[210:213], v[74:77]
	v_mfma_f32_16x16x32_bf16 v[150:153], v[118:121], v[166:169], v[150:153]
	v_mfma_f32_16x16x32_bf16 v[146:149], v[134:137], v[166:169], v[146:149]
	v_mfma_f32_16x16x32_bf16 v[126:129], v[118:121], v[192:195], v[126:129]
	v_mfma_f32_16x16x32_bf16 v[122:125], v[134:137], v[192:195], v[122:125]
	v_mfma_f32_16x16x32_bf16 v[102:105], v[118:121], v[206:209], v[102:105]
	v_mfma_f32_16x16x32_bf16 v[98:101], v[134:137], v[206:209], v[98:101]
	v_mfma_f32_16x16x32_bf16 v[78:81], v[118:121], v[214:217], v[78:81]
	v_mfma_f32_16x16x32_bf16 v[74:77], v[134:137], v[214:217], v[74:77]
	s_setprio 0
	s_barrier
; #define PG8_STAGE(bufoff, gbase, voff) do { _Pragma("unroll") for (int _i = 0; _i < 2; ++_i) \
;         __builtin_amdgcn_global_load_lds((const unsigned*)((const char*)(gbase) + (voff)[_i]), (PG8_LAS unsigned*)(lds + (bufoff) + ldsw + _i * 8192), 16, 0, 0); } while (0)
; #define PG8_LDA(dst, b, h) do { _Pragma("unroll") for (int m = 0; m < 4; ++m) _Pragma("unroll") for (int k = 0; k < 2; ++k) dst[m][k] = *(const PG8_LAS bf16x8*)(lds + PG8_SA(b, h) + aoff + m * 2048 + k * 1024); } while (0)
; #define PG8_MMA(ai, bj, At, Bt) do { __builtin_amdgcn_s_setprio(1); _Pragma("unroll") for (int m = 0; m < 4; ++m) _Pragma("unroll") for (int n = 0; n < 2; ++n) _Pragma("unroll") for (int k = 0; k < 2; ++k) \
;         acc[ai][bj][m][n] = __builtin_amdgcn_mfma_f32_16x16x32_bf16(Bt[n][k], At[m][k], acc[ai][bj][m][n], 0, 0, 0); __builtin_amdgcn_s_setprio(0); } while (0)
; #define PG8_WAIT_V(n) asm volatile("s_waitcnt vmcnt(" #n ")" ::: "memory")
; #define PG8_WAIT_L(n) asm volatile("s_waitcnt lgkmcnt(" #n ")" ::: "memory")
; #define PG8_BAR __builtin_amdgcn_s_barrier()
; #define PG8_SCHED __builtin_amdgcn_sched_barrier(0)
; template <class Epi, class Sched, bool ALIGN_EPI = false, bool SP2 = false>
; __device__ __forceinline__ void gemm_phase(PG8_LAS unsigned char* lds, const Gemm g, const Sched& S, const Epi& E) {
;     ...
;         for (int t = 0; t < nt; t += 2) {
;     ...
;             PG8_LDA(At, 1, 1); PG8_STAGE(PG8_SB(1, 0), b3, voffB); PG8_STAGE(PG8_SB(1, 1), b3 + hstep, voffB); PG8_STAGE(PG8_SA(1, 0), a3, voffA);
;             PG8_WAIT_V(8); PG8_WAIT_L(0); PG8_BAR; PG8_MMA(1, 0, At, B0); PG8_MMA(1, 1, At, B1); PG8_BAR; PG8_SCHED;
	s_add_i32 s36, s56, s42
	v_lshl_add_u64 v[200:201], v[200:201], 0, s[96:97]
	s_mov_b32 m0, s36
	ds_read_b128 v[162:165], v204 offset:49152
	ds_read_b128 v[166:169], v204 offset:50176
	ds_read_b128 v[188:191], v204 offset:51200
	ds_read_b128 v[192:195], v204 offset:52224
	ds_read_b128 v[196:199], v204 offset:53248
	ds_read_b128 v[206:209], v204 offset:54272
	ds_read_b128 v[210:213], v204 offset:55296
	ds_read_b128 v[214:217], v204 offset:56320
	global_load_lds_dwordx4 v[200:201], off
	s_add_i32 m0, s36, 0x2000
	s_add_u32 s10, s10, 0x40080
	v_lshl_add_u64 v[200:201], v[218:219], 0, s[96:97]
	s_addc_u32 s11, s11, 0
	s_add_i32 s36, s57, s42
	global_load_lds_dwordx4 v[200:201], off
	v_lshl_add_u64 v[200:201], s[10:11], 0, v[180:181]
	s_mov_b32 m0, s36
	s_nop 0
	global_load_lds_dwordx4 v[200:201], off
	v_lshl_add_u64 v[200:201], s[10:11], 0, v[170:171]
	s_add_i32 m0, s36, 0x2000
	s_nop 0
	global_load_lds_dwordx4 v[200:201], off
	v_lshl_add_u64 v[200:201], v[220:221], 0, s[96:97]
	s_mov_b32 m0, s50
	s_nop 0
	global_load_lds_dwordx4 v[200:201], off
	v_lshl_add_u64 v[200:201], v[222:223], 0, s[96:97]
	s_mov_b32 m0, s51
	s_nop 0
	global_load_lds_dwordx4 v[200:201], off
	s_waitcnt vmcnt(8)
	s_waitcnt lgkmcnt(0)
	s_barrier
	s_setprio 1
	s_waitcnt lgkmcnt(0)
	v_mfma_f32_16x16x32_bf16 v[62:65], v[66:69], v[162:165], v[62:65]
	v_mfma_f32_16x16x32_bf16 v[58:61], v[82:85], v[162:165], v[58:61]
	v_mfma_f32_16x16x32_bf16 v[46:49], v[66:69], v[188:191], v[46:49]
	v_mfma_f32_16x16x32_bf16 v[42:45], v[82:85], v[188:191], v[42:45]
	v_mfma_f32_16x16x32_bf16 v[30:33], v[66:69], v[196:199], v[30:33]
	v_mfma_f32_16x16x32_bf16 v[26:29], v[82:85], v[196:199], v[26:29]
	v_mfma_f32_16x16x32_bf16 v[14:17], v[66:69], v[210:213], v[14:17]
	v_mfma_f32_16x16x32_bf16 v[10:13], v[82:85], v[210:213], v[10:13]
	v_mfma_f32_16x16x32_bf16 v[62:65], v[70:73], v[166:169], v[62:65]
	v_mfma_f32_16x16x32_bf16 v[58:61], v[94:97], v[166:169], v[58:61]
	v_mfma_f32_16x16x32_bf16 v[46:49], v[70:73], v[192:195], v[46:49]
	v_mfma_f32_16x16x32_bf16 v[42:45], v[94:97], v[192:195], v[42:45]
	v_mfma_f32_16x16x32_bf16 v[30:33], v[70:73], v[206:209], v[30:33]
	v_mfma_f32_16x16x32_bf16 v[26:29], v[94:97], v[206:209], v[26:29]
	v_mfma_f32_16x16x32_bf16 v[14:17], v[70:73], v[214:217], v[14:17]
	v_mfma_f32_16x16x32_bf16 v[10:13], v[94:97], v[214:217], v[10:13]
	v_mfma_f32_16x16x32_bf16 v[54:57], v[106:109], v[162:165], v[54:57]
	v_mfma_f32_16x16x32_bf16 v[50:53], v[130:133], v[162:165], v[50:53]
	v_mfma_f32_16x16x32_bf16 v[38:41], v[106:109], v[188:191], v[38:41]
	v_mfma_f32_16x16x32_bf16 v[34:37], v[130:133], v[188:191], v[34:37]
	v_mfma_f32_16x16x32_bf16 v[22:25], v[106:109], v[196:199], v[22:25]
	v_mfma_f32_16x16x32_bf16 v[18:21], v[130:133], v[196:199], v[18:21]
	v_mfma_f32_16x16x32_bf16 v[6:9], v[106:109], v[210:213], v[6:9]
	v_mfma_f32_16x16x32_bf16 v[2:5], v[130:133], v[210:213], v[2:5]
	v_mfma_f32_16x16x32_bf16 v[54:57], v[118:121], v[166:169], v[54:57]
	v_mfma_f32_16x16x32_bf16 v[50:53], v[134:137], v[166:169], v[50:53]
	v_mfma_f32_16x16x32_bf16 v[38:41], v[118:121], v[192:195], v[38:41]
	v_mfma_f32_16x16x32_bf16 v[34:37], v[134:137], v[192:195], v[34:37]
	v_mfma_f32_16x16x32_bf16 v[22:25], v[118:121], v[206:209], v[22:25]
	v_mfma_f32_16x16x32_bf16 v[18:21], v[134:137], v[206:209], v[18:21]
	v_mfma_f32_16x16x32_bf16 v[6:9], v[118:121], v[214:217], v[6:9]
	v_mfma_f32_16x16x32_bf16 v[2:5], v[134:137], v[214:217], v[2:5]
	s_setprio 0
	s_barrier
	s_add_i32 s55, s55, 2
	s_add_u32 s8, s8, 0x100
	s_addc_u32 s9, s9, 0
	s_add_u32 s33, s33, 0x100
	s_addc_u32 s54, s54, 0
	s_cmp_gt_u32 s55, 13
	s_cbranch_scc0 .LBB0_1075
	s_and_b64 vcc, exec, s[20:21]
	s_cbranch_vccz .LBB0_1078
	s_barrier

; #define PG8_STAGE(bufoff, gbase, voff) do { _Pragma("unroll") for (int _i = 0; _i < 2; ++_i) \
;         __builtin_amdgcn_global_load_lds((const unsigned*)((const char*)(gbase) + (voff)[_i]), (PG8_LAS unsigned*)(lds + (bufoff) + ldsw + _i * 8192), 16, 0, 0); } while (0)
; #define PG8_LDA(dst, b, h) do { _Pragma("unroll") for (int m = 0; m < 4; ++m) _Pragma("unroll") for (int k = 0; k < 2; ++k) dst[m][k] = *(const PG8_LAS bf16x8*)(lds + PG8_SA(b, h) + aoff + m * 2048 + k * 1024); } while (0)
; #define PG8_MMA(ai, bj, At, Bt) do { __builtin_amdgcn_s_setprio(1); _Pragma("unroll") for (int m = 0; m < 4; ++m) _Pragma("unroll") for (int n = 0; n < 2; ++n) _Pragma("unroll") for (int k = 0; k < 2; ++k) \
;         acc[ai][bj][m][n] = __builtin_amdgcn_mfma_f32_16x16x32_bf16(Bt[n][k], At[m][k], acc[ai][bj][m][n], 0, 0, 0); __builtin_amdgcn_s_setprio(0); } while (0)
; #define PG8_WAIT_V(n) asm volatile("s_waitcnt vmcnt(" #n ")" ::: "memory")
; #define PG8_WAIT_L(n) asm volatile("s_waitcnt lgkmcnt(" #n ")" ::: "memory")
; #define PG8_BAR __builtin_amdgcn_s_barrier()
; #define PG8_SCHED __builtin_amdgcn_sched_barrier(0)
; template <class Epi, class Sched, bool ALIGN_EPI = false, bool SP2 = false>
; __device__ __forceinline__ void gemm_phase(PG8_LAS unsigned char* lds, const Gemm g, const Sched& S, const Epi& E) {
;     ...
;             PG8_WAIT_V(8); PG8_WAIT_L(0); PG8_BAR; PG8_MMA(0, 0, At, B0); PG8_MMA(0, 1, At, B1); PG8_BAR; PG8_SCHED;
;             PG8_LDA(At, 0, 1); PG8_STAGE(PG8_SB(0, 0), b2, voffB); PG8_STAGE(PG8_SB(0, 1), b2 + hstep, voffB); PG8_STAGE(PG8_SA(0, 0), a2, voffA);
.Lffin_noz:
	s_waitcnt vmcnt(8)
	s_waitcnt lgkmcnt(0)
	s_barrier
	s_setprio 1
	s_waitcnt lgkmcnt(0)
	v_mfma_f32_16x16x32_bf16 v[158:161], v[106:109], v[162:165], v[158:161]
	v_mfma_f32_16x16x32_bf16 v[154:157], v[114:117], v[162:165], v[154:157]
	v_mfma_f32_16x16x32_bf16 v[142:145], v[106:109], v[170:173], v[142:145]
	v_mfma_f32_16x16x32_bf16 v[138:141], v[114:117], v[170:173], v[138:141]
	v_mfma_f32_16x16x32_bf16 v[94:97], v[106:109], v[196:199], v[94:97]
	v_mfma_f32_16x16x32_bf16 v[90:93], v[114:117], v[196:199], v[90:93]
	v_mfma_f32_16x16x32_bf16 v[78:81], v[106:109], v[204:207], v[78:81]
	v_mfma_f32_16x16x32_bf16 v[74:77], v[114:117], v[204:207], v[74:77]
	v_mfma_f32_16x16x32_bf16 v[158:161], v[110:113], v[166:169], v[158:161]
	v_mfma_f32_16x16x32_bf16 v[154:157], v[118:121], v[166:169], v[154:157]
	v_mfma_f32_16x16x32_bf16 v[142:145], v[110:113], v[192:195], v[142:145]
	v_mfma_f32_16x16x32_bf16 v[138:141], v[118:121], v[192:195], v[138:141]
	v_mfma_f32_16x16x32_bf16 v[94:97], v[110:113], v[200:203], v[94:97]
	v_mfma_f32_16x16x32_bf16 v[90:93], v[118:121], v[200:203], v[90:93]
	v_mfma_f32_16x16x32_bf16 v[78:81], v[110:113], v[208:211], v[78:81]
	v_mfma_f32_16x16x32_bf16 v[74:77], v[118:121], v[208:211], v[74:77]
	v_mfma_f32_16x16x32_bf16 v[150:153], v[122:125], v[162:165], v[150:153]
	v_mfma_f32_16x16x32_bf16 v[146:149], v[130:133], v[162:165], v[146:149]
	v_mfma_f32_16x16x32_bf16 v[102:105], v[122:125], v[170:173], v[102:105]
	v_mfma_f32_16x16x32_bf16 v[98:101], v[130:133], v[170:173], v[98:101]
	v_mfma_f32_16x16x32_bf16 v[86:89], v[122:125], v[196:199], v[86:89]
	v_mfma_f32_16x16x32_bf16 v[82:85], v[130:133], v[196:199], v[82:85]
	v_mfma_f32_16x16x32_bf16 v[70:73], v[122:125], v[204:207], v[70:73]
	v_mfma_f32_16x16x32_bf16 v[66:69], v[130:133], v[204:207], v[66:69]
	v_mfma_f32_16x16x32_bf16 v[150:153], v[126:129], v[166:169], v[150:153]
	v_mfma_f32_16x16x32_bf16 v[146:149], v[134:137], v[166:169], v[146:149]
	v_mfma_f32_16x16x32_bf16 v[102:105], v[126:129], v[192:195], v[102:105]
	v_mfma_f32_16x16x32_bf16 v[98:101], v[134:137], v[192:195], v[98:101]
	v_mfma_f32_16x16x32_bf16 v[86:89], v[126:129], v[200:203], v[86:89]
	v_mfma_f32_16x16x32_bf16 v[82:85], v[134:137], v[200:203], v[82:85]
	v_mfma_f32_16x16x32_bf16 v[70:73], v[126:129], v[208:211], v[70:73]
	v_mfma_f32_16x16x32_bf16 v[66:69], v[134:137], v[208:211], v[66:69]
	s_setprio 0
	s_barrier
	s_add_i32 s69, s69, s52
	v_lshl_add_u64 v[212:213], s[44:45], 0, v[184:185]
	s_mov_b32 m0, s69
	ds_read_b128 v[162:165], v230 offset:16384
	ds_read_b128 v[166:169], v230 offset:17408
	ds_read_b128 v[170:173], v230 offset:18432
	ds_read_b128 v[192:195], v230 offset:19456
	ds_read_b128 v[196:199], v230 offset:20480
	ds_read_b128 v[200:203], v230 offset:21504
	ds_read_b128 v[204:207], v230 offset:22528
	ds_read_b128 v[208:211], v230 offset:23552
	global_load_lds_dwordx4 v[212:213], off
	s_add_i32 m0, s69, 0x2000
	s_add_u32 s70, s44, 0x40000
	v_lshl_add_u64 v[214:215], s[44:45], 0, v[180:181]
	s_addc_u32 s71, s45, 0
	s_add_i32 s69, s72, s52
	global_load_lds_dwordx4 v[214:215], off
	v_lshl_add_u64 v[216:217], s[70:71], 0, v[184:185]
	s_mov_b32 m0, s69
	v_lshl_add_u64 v[218:219], s[46:47], 0, v[182:183]
	global_load_lds_dwordx4 v[216:217], off
	v_lshl_add_u64 v[216:217], s[70:71], 0, v[180:181]
	s_add_i32 m0, s69, 0x2000
	s_nop 0
	global_load_lds_dwordx4 v[216:217], off
	v_lshl_add_u64 v[216:217], s[46:47], 0, v[186:187]
	s_mov_b32 m0, s53
	s_nop 0
	global_load_lds_dwordx4 v[216:217], off
	s_mov_b32 m0, s54
	s_nop 0
	global_load_lds_dwordx4 v[218:219], off
	s_cmp_lg_u32 s68, -2
	s_cbranch_scc1 .Lffin_w8
	s_cmp_lt_u32 s57, 2
	s_cbranch_scc1 .Lffin_w8
	s_waitcnt vmcnt(16)
	s_branch .Lffin_wd

; #define PG8_STAGE(bufoff, gbase, voff) do { _Pragma("unroll") for (int _i = 0; _i < 2; ++_i) \
;         __builtin_amdgcn_global_load_lds((const unsigned*)((const char*)(gbase) + (voff)[_i]), (PG8_LAS unsigned*)(lds + (bufoff) + ldsw + _i * 8192), 16, 0, 0); } while (0)
; #define PG8_LDA(dst, b, h) do { _Pragma("unroll") for (int m = 0; m < 4; ++m) _Pragma("unroll") for (int k = 0; k < 2; ++k) dst[m][k] = *(const PG8_LAS bf16x8*)(lds + PG8_SA(b, h) + aoff + m * 2048 + k * 1024); } while (0)
; #define PG8_LDB(dst, b, h) do { _Pragma("unroll") for (int n = 0; n < 2; ++n) _Pragma("unroll") for (int k = 0; k < 2; ++k) dst[n][k] = *(const PG8_LAS bf16x8*)(lds + PG8_SB(b, h) + boff + n * 2048 + k * 1024); } while (0)
; #define PG8_MMA(ai, bj, At, Bt) do { __builtin_amdgcn_s_setprio(1); _Pragma("unroll") for (int m = 0; m < 4; ++m) _Pragma("unroll") for (int n = 0; n < 2; ++n) _Pragma("unroll") for (int k = 0; k < 2; ++k) \
;         acc[ai][bj][m][n] = __builtin_amdgcn_mfma_f32_16x16x32_bf16(Bt[n][k], At[m][k], acc[ai][bj][m][n], 0, 0, 0); __builtin_amdgcn_s_setprio(0); } while (0)
; #define PG8_WAIT_V(n) asm volatile("s_waitcnt vmcnt(" #n ")" ::: "memory")
; #define PG8_WAIT_L(n) asm volatile("s_waitcnt lgkmcnt(" #n ")" ::: "memory")
; #define PG8_BAR __builtin_amdgcn_s_barrier()
; #define PG8_SCHED __builtin_amdgcn_sched_barrier(0)
; template <class Epi, class Sched, bool ALIGN_EPI = false, bool SP2 = false>
; __device__ __forceinline__ void gemm_phase(PG8_LAS unsigned char* lds, const Gemm g, const Sched& S, const Epi& E) {
;     ...
;             PG8_WAIT_V(8); PG8_WAIT_L(0); PG8_BAR; PG8_MMA(1, 0, At, B0); PG8_MMA(1, 1, At, B1); PG8_BAR; PG8_SCHED;
;             PG8_LDB(B0, 1, 0); PG8_LDB(B1, 1, 1); PG8_SCHED; PG8_LDA(At, 1, 0); PG8_STAGE(PG8_SA(0, 1), a2 + hstep, voffA);
;             PG8_WAIT_V(8); PG8_WAIT_L(0); PG8_BAR; PG8_MMA(0, 0, At, B0); PG8_MMA(0, 1, At, B1); PG8_BAR; PG8_SCHED;
.Lffin_wd:
	s_waitcnt lgkmcnt(0)
	s_barrier
	s_setprio 1
	s_waitcnt lgkmcnt(0)
	v_mfma_f32_16x16x32_bf16 v[62:65], v[106:109], v[162:165], v[62:65]
	v_mfma_f32_16x16x32_bf16 v[58:61], v[114:117], v[162:165], v[58:61]
	v_mfma_f32_16x16x32_bf16 v[46:49], v[106:109], v[170:173], v[46:49]
	v_mfma_f32_16x16x32_bf16 v[42:45], v[114:117], v[170:173], v[42:45]
	v_mfma_f32_16x16x32_bf16 v[30:33], v[106:109], v[196:199], v[30:33]
	v_mfma_f32_16x16x32_bf16 v[26:29], v[114:117], v[196:199], v[26:29]
	v_mfma_f32_16x16x32_bf16 v[14:17], v[106:109], v[204:207], v[14:17]
	v_mfma_f32_16x16x32_bf16 v[10:13], v[114:117], v[204:207], v[10:13]
	v_mfma_f32_16x16x32_bf16 v[62:65], v[110:113], v[166:169], v[62:65]
	v_mfma_f32_16x16x32_bf16 v[58:61], v[118:121], v[166:169], v[58:61]
	v_mfma_f32_16x16x32_bf16 v[46:49], v[110:113], v[192:195], v[46:49]
	v_mfma_f32_16x16x32_bf16 v[42:45], v[118:121], v[192:195], v[42:45]
	v_mfma_f32_16x16x32_bf16 v[30:33], v[110:113], v[200:203], v[30:33]
	v_mfma_f32_16x16x32_bf16 v[26:29], v[118:121], v[200:203], v[26:29]
	v_mfma_f32_16x16x32_bf16 v[14:17], v[110:113], v[208:211], v[14:17]
	v_mfma_f32_16x16x32_bf16 v[10:13], v[118:121], v[208:211], v[10:13]
	v_mfma_f32_16x16x32_bf16 v[54:57], v[122:125], v[162:165], v[54:57]
	v_mfma_f32_16x16x32_bf16 v[50:53], v[130:133], v[162:165], v[50:53]
	v_mfma_f32_16x16x32_bf16 v[38:41], v[122:125], v[170:173], v[38:41]
	v_mfma_f32_16x16x32_bf16 v[34:37], v[130:133], v[170:173], v[34:37]
	v_mfma_f32_16x16x32_bf16 v[22:25], v[122:125], v[196:199], v[22:25]
	v_mfma_f32_16x16x32_bf16 v[18:21], v[130:133], v[196:199], v[18:21]
	v_mfma_f32_16x16x32_bf16 v[6:9], v[122:125], v[204:207], v[6:9]
	v_mfma_f32_16x16x32_bf16 v[2:5], v[130:133], v[204:207], v[2:5]
	v_mfma_f32_16x16x32_bf16 v[54:57], v[126:129], v[166:169], v[54:57]
	v_mfma_f32_16x16x32_bf16 v[50:53], v[134:137], v[166:169], v[50:53]
	v_mfma_f32_16x16x32_bf16 v[38:41], v[126:129], v[192:195], v[38:41]
	v_mfma_f32_16x16x32_bf16 v[34:37], v[134:137], v[192:195], v[34:37]
	v_mfma_f32_16x16x32_bf16 v[22:25], v[126:129], v[200:203], v[22:25]
	v_mfma_f32_16x16x32_bf16 v[18:21], v[134:137], v[200:203], v[18:21]
	v_mfma_f32_16x16x32_bf16 v[6:9], v[126:129], v[208:211], v[6:9]
	v_mfma_f32_16x16x32_bf16 v[2:5], v[134:137], v[208:211], v[2:5]
	s_setprio 0
	s_barrier
	s_add_i32 s69, 0, 0x18000
	s_add_i32 s70, 0, 0x1c000
	v_add_u32_e32 v118, s69, v229
	v_add_u32_e32 v134, s70, v229
	ds_read_b128 v[106:109], v118
	ds_read_b128 v[110:113], v118 offset:1024
	ds_read_b128 v[114:117], v118 offset:2048
	ds_read_b128 v[118:121], v118 offset:3072
	ds_read_b128 v[122:125], v134
	ds_read_b128 v[126:129], v134 offset:1024
	ds_read_b128 v[130:133], v134 offset:2048
	ds_read_b128 v[134:137], v134 offset:3072
	s_add_u32 s46, s46, 0x40000
	s_addc_u32 s47, s47, 0
	s_mov_b32 m0, s55
	v_lshl_add_u64 v[220:221], s[46:47], 0, v[186:187]
	ds_read_b128 v[162:165], v230 offset:32768
	ds_read_b128 v[166:169], v230 offset:33792
	ds_read_b128 v[170:173], v230 offset:34816
	ds_read_b128 v[192:195], v230 offset:35840
	ds_read_b128 v[196:199], v230 offset:36864
	ds_read_b128 v[200:203], v230 offset:37888
	ds_read_b128 v[204:207], v230 offset:38912
	ds_read_b128 v[208:211], v230 offset:39936
	global_load_lds_dwordx4 v[220:221], off
	v_lshl_add_u64 v[220:221], s[46:47], 0, v[182:183]
	s_mov_b32 m0, s56
	s_nop 0
	global_load_lds_dwordx4 v[220:221], off
	s_waitcnt vmcnt(8)
	s_waitcnt lgkmcnt(0)
	s_barrier
	s_setprio 1
	s_waitcnt lgkmcnt(0)
	v_mfma_f32_16x16x32_bf16 v[158:161], v[106:109], v[162:165], v[158:161]
	v_mfma_f32_16x16x32_bf16 v[154:157], v[114:117], v[162:165], v[154:157]
	v_mfma_f32_16x16x32_bf16 v[142:145], v[106:109], v[170:173], v[142:145]
	v_mfma_f32_16x16x32_bf16 v[138:141], v[114:117], v[170:173], v[138:141]
	v_mfma_f32_16x16x32_bf16 v[94:97], v[106:109], v[196:199], v[94:97]
	v_mfma_f32_16x16x32_bf16 v[90:93], v[114:117], v[196:199], v[90:93]
	v_mfma_f32_16x16x32_bf16 v[78:81], v[106:109], v[204:207], v[78:81]
	v_mfma_f32_16x16x32_bf16 v[74:77], v[114:117], v[204:207], v[74:77]
	v_mfma_f32_16x16x32_bf16 v[158:161], v[110:113], v[166:169], v[158:161]
	v_mfma_f32_16x16x32_bf16 v[154:157], v[118:121], v[166:169], v[154:157]
	v_mfma_f32_16x16x32_bf16 v[142:145], v[110:113], v[192:195], v[142:145]
	v_mfma_f32_16x16x32_bf16 v[138:141], v[118:121], v[192:195], v[138:141]
	v_mfma_f32_16x16x32_bf16 v[94:97], v[110:113], v[200:203], v[94:97]
	v_mfma_f32_16x16x32_bf16 v[90:93], v[118:121], v[200:203], v[90:93]
	v_mfma_f32_16x16x32_bf16 v[78:81], v[110:113], v[208:211], v[78:81]
	v_mfma_f32_16x16x32_bf16 v[74:77], v[118:121], v[208:211], v[74:77]
	v_mfma_f32_16x16x32_bf16 v[150:153], v[122:125], v[162:165], v[150:153]
	v_mfma_f32_16x16x32_bf16 v[146:149], v[130:133], v[162:165], v[146:149]
	v_mfma_f32_16x16x32_bf16 v[102:105], v[122:125], v[170:173], v[102:105]
	v_mfma_f32_16x16x32_bf16 v[98:101], v[130:133], v[170:173], v[98:101]
	v_mfma_f32_16x16x32_bf16 v[86:89], v[122:125], v[196:199], v[86:89]
	v_mfma_f32_16x16x32_bf16 v[82:85], v[130:133], v[196:199], v[82:85]
	v_mfma_f32_16x16x32_bf16 v[70:73], v[122:125], v[204:207], v[70:73]
	v_mfma_f32_16x16x32_bf16 v[66:69], v[130:133], v[204:207], v[66:69]
	v_mfma_f32_16x16x32_bf16 v[150:153], v[126:129], v[166:169], v[150:153]
	v_mfma_f32_16x16x32_bf16 v[146:149], v[134:137], v[166:169], v[146:149]
	v_mfma_f32_16x16x32_bf16 v[102:105], v[126:129], v[192:195], v[102:105]
	v_mfma_f32_16x16x32_bf16 v[98:101], v[134:137], v[192:195], v[98:101]
	v_mfma_f32_16x16x32_bf16 v[86:89], v[126:129], v[200:203], v[86:89]
	v_mfma_f32_16x16x32_bf16 v[82:85], v[134:137], v[200:203], v[82:85]
	v_mfma_f32_16x16x32_bf16 v[70:73], v[126:129], v[208:211], v[70:73]
	v_mfma_f32_16x16x32_bf16 v[66:69], v[134:137], v[208:211], v[66:69]
	s_setprio 0
	s_barrier
; #define PG8_STAGE(bufoff, gbase, voff) do { _Pragma("unroll") for (int _i = 0; _i < 2; ++_i) \
;         __builtin_amdgcn_global_load_lds((const unsigned*)((const char*)(gbase) + (voff)[_i]), (PG8_LAS unsigned*)(lds + (bufoff) + ldsw + _i * 8192), 16, 0, 0); } while (0)
; #define PG8_LDA(dst, b, h) do { _Pragma("unroll") for (int m = 0; m < 4; ++m) _Pragma("unroll") for (int k = 0; k < 2; ++k) dst[m][k] = *(const PG8_LAS bf16x8*)(lds + PG8_SA(b, h) + aoff + m * 2048 + k * 1024); } while (0)
; #define PG8_MMA(ai, bj, At, Bt) do { __builtin_amdgcn_s_setprio(1); _Pragma("unroll") for (int m = 0; m < 4; ++m) _Pragma("unroll") for (int n = 0; n < 2; ++n) _Pragma("unroll") for (int k = 0; k < 2; ++k) \
;         acc[ai][bj][m][n] = __builtin_amdgcn_mfma_f32_16x16x32_bf16(Bt[n][k], At[m][k], acc[ai][bj][m][n], 0, 0, 0); __builtin_amdgcn_s_setprio(0); } while (0)
; #define PG8_WAIT_V(n) asm volatile("s_waitcnt vmcnt(" #n ")" ::: "memory")
; #define PG8_WAIT_L(n) asm volatile("s_waitcnt lgkmcnt(" #n ")" ::: "memory")
; #define PG8_BAR __builtin_amdgcn_s_barrier()
; #define PG8_SCHED __builtin_amdgcn_sched_barrier(0)
; template <class Epi, class Sched, bool ALIGN_EPI = false, bool SP2 = false>
; __device__ __forceinline__ void gemm_phase(PG8_LAS unsigned char* lds, const Gemm g, const Sched& S, const Epi& E) {
;     ...
;         for (int t = 0; t < nt; t += 2) {
;     ...
;             PG8_LDA(At, 1, 1); PG8_STAGE(PG8_SB(1, 0), b3, voffB); PG8_STAGE(PG8_SB(1, 1), b3 + hstep, voffB); PG8_STAGE(PG8_SA(1, 0), a3, voffA);
;             PG8_WAIT_V(8); PG8_WAIT_L(0); PG8_BAR; PG8_MMA(1, 0, At, B0); PG8_MMA(1, 1, At, B1); PG8_BAR; PG8_SCHED;
	s_add_i32 s46, s69, s52
	v_lshl_add_u64 v[212:213], v[212:213], 0, s[96:97]
	s_mov_b32 m0, s46
	ds_read_b128 v[162:165], v230 offset:49152
	ds_read_b128 v[166:169], v230 offset:50176
	ds_read_b128 v[170:173], v230 offset:51200
	ds_read_b128 v[192:195], v230 offset:52224
	ds_read_b128 v[196:199], v230 offset:53248
	ds_read_b128 v[200:203], v230 offset:54272
	ds_read_b128 v[204:207], v230 offset:55296
	ds_read_b128 v[208:211], v230 offset:56320
	global_load_lds_dwordx4 v[212:213], off
	s_add_i32 m0, s46, 0x2000
	s_add_u32 s44, s44, 0x40080
	v_lshl_add_u64 v[212:213], v[214:215], 0, s[96:97]
	s_addc_u32 s45, s45, 0
	s_add_i32 s46, s70, s52
	global_load_lds_dwordx4 v[212:213], off
	v_lshl_add_u64 v[212:213], s[44:45], 0, v[184:185]
	s_mov_b32 m0, s46
	s_nop 0
	global_load_lds_dwordx4 v[212:213], off
	v_lshl_add_u64 v[212:213], s[44:45], 0, v[180:181]
	s_add_i32 m0, s46, 0x2000
	s_nop 0
	global_load_lds_dwordx4 v[212:213], off
	v_lshl_add_u64 v[212:213], v[216:217], 0, s[96:97]
	s_mov_b32 m0, s60
	s_nop 0
	global_load_lds_dwordx4 v[212:213], off
	v_lshl_add_u64 v[212:213], v[218:219], 0, s[96:97]
	s_mov_b32 m0, s61
	s_nop 0
	global_load_lds_dwordx4 v[212:213], off
	s_waitcnt vmcnt(8)
	s_waitcnt lgkmcnt(0)
	s_barrier
	s_setprio 1
	s_waitcnt lgkmcnt(0)
	v_mfma_f32_16x16x32_bf16 v[62:65], v[106:109], v[162:165], v[62:65]
	v_mfma_f32_16x16x32_bf16 v[58:61], v[114:117], v[162:165], v[58:61]
	v_mfma_f32_16x16x32_bf16 v[46:49], v[106:109], v[170:173], v[46:49]
	v_mfma_f32_16x16x32_bf16 v[42:45], v[114:117], v[170:173], v[42:45]
	v_mfma_f32_16x16x32_bf16 v[30:33], v[106:109], v[196:199], v[30:33]
	v_mfma_f32_16x16x32_bf16 v[26:29], v[114:117], v[196:199], v[26:29]
	v_mfma_f32_16x16x32_bf16 v[14:17], v[106:109], v[204:207], v[14:17]
	v_mfma_f32_16x16x32_bf16 v[10:13], v[114:117], v[204:207], v[10:13]
	v_mfma_f32_16x16x32_bf16 v[62:65], v[110:113], v[166:169], v[62:65]
	v_mfma_f32_16x16x32_bf16 v[58:61], v[118:121], v[166:169], v[58:61]
	v_mfma_f32_16x16x32_bf16 v[46:49], v[110:113], v[192:195], v[46:49]
	v_mfma_f32_16x16x32_bf16 v[42:45], v[118:121], v[192:195], v[42:45]
	v_mfma_f32_16x16x32_bf16 v[30:33], v[110:113], v[200:203], v[30:33]
	v_mfma_f32_16x16x32_bf16 v[26:29], v[118:121], v[200:203], v[26:29]
	v_mfma_f32_16x16x32_bf16 v[14:17], v[110:113], v[208:211], v[14:17]
	v_mfma_f32_16x16x32_bf16 v[10:13], v[118:121], v[208:211], v[10:13]
	v_mfma_f32_16x16x32_bf16 v[54:57], v[122:125], v[162:165], v[54:57]
	v_mfma_f32_16x16x32_bf16 v[50:53], v[130:133], v[162:165], v[50:53]
	v_mfma_f32_16x16x32_bf16 v[38:41], v[122:125], v[170:173], v[38:41]
	v_mfma_f32_16x16x32_bf16 v[34:37], v[130:133], v[170:173], v[34:37]
	v_mfma_f32_16x16x32_bf16 v[22:25], v[122:125], v[196:199], v[22:25]
	v_mfma_f32_16x16x32_bf16 v[18:21], v[130:133], v[196:199], v[18:21]
	v_mfma_f32_16x16x32_bf16 v[6:9], v[122:125], v[204:207], v[6:9]
	v_mfma_f32_16x16x32_bf16 v[2:5], v[130:133], v[204:207], v[2:5]
	v_mfma_f32_16x16x32_bf16 v[54:57], v[126:129], v[166:169], v[54:57]
	v_mfma_f32_16x16x32_bf16 v[50:53], v[134:137], v[166:169], v[50:53]
	v_mfma_f32_16x16x32_bf16 v[38:41], v[126:129], v[192:195], v[38:41]
	v_mfma_f32_16x16x32_bf16 v[34:37], v[134:137], v[192:195], v[34:37]
	v_mfma_f32_16x16x32_bf16 v[22:25], v[126:129], v[200:203], v[22:25]
	v_mfma_f32_16x16x32_bf16 v[18:21], v[134:137], v[200:203], v[18:21]
	v_mfma_f32_16x16x32_bf16 v[6:9], v[126:129], v[208:211], v[6:9]
	v_mfma_f32_16x16x32_bf16 v[2:5], v[134:137], v[208:211], v[2:5]
	s_setprio 0
	s_barrier
	s_add_i32 s68, s68, 2
	s_add_u32 s8, s8, 0x100
	s_addc_u32 s9, s9, 0
	s_add_u32 s66, s66, 0x100
	s_addc_u32 s67, s67, 0
	s_cmp_gt_u32 s68, 13
	s_cbranch_scc0 .LBB0_1247
	s_and_b64 vcc, exec, s[24:25]
	s_cbranch_vccz .LBB0_1250
	s_barrier

; #define PG8_STAGE(bufoff, gbase, voff) do { _Pragma("unroll") for (int _i = 0; _i < 2; ++_i) \
;         __builtin_amdgcn_global_load_lds((const unsigned*)((const char*)(gbase) + (voff)[_i]), (PG8_LAS unsigned*)(lds + (bufoff) + ldsw + _i * 8192), 16, 0, 0); } while (0)
; #define PG8_LDA(dst, b, h) do { _Pragma("unroll") for (int m = 0; m < 4; ++m) _Pragma("unroll") for (int k = 0; k < 2; ++k) dst[m][k] = *(const PG8_LAS bf16x8*)(lds + PG8_SA(b, h) + aoff + m * 2048 + k * 1024); } while (0)
; #define PG8_MMA(ai, bj, At, Bt) do { __builtin_amdgcn_s_setprio(1); _Pragma("unroll") for (int m = 0; m < 4; ++m) _Pragma("unroll") for (int n = 0; n < 2; ++n) _Pragma("unroll") for (int k = 0; k < 2; ++k) \
;         acc[ai][bj][m][n] = __builtin_amdgcn_mfma_f32_16x16x32_bf16(Bt[n][k], At[m][k], acc[ai][bj][m][n], 0, 0, 0); __builtin_amdgcn_s_setprio(0); } while (0)
; #define PG8_WAIT_V(n) asm volatile("s_waitcnt vmcnt(" #n ")" ::: "memory")
; #define PG8_WAIT_L(n) asm volatile("s_waitcnt lgkmcnt(" #n ")" ::: "memory")
; #define PG8_BAR __builtin_amdgcn_s_barrier()
; #define PG8_SCHED __builtin_amdgcn_sched_barrier(0)
; template <class Epi, class Sched, bool ALIGN_EPI = false, bool SP2 = false>
; __device__ __forceinline__ void gemm_phase(PG8_LAS unsigned char* lds, const Gemm g, const Sched& S, const Epi& E) {
;     ...
;             PG8_WAIT_V(8); PG8_WAIT_L(0); PG8_BAR; PG8_MMA(0, 0, At, B0); PG8_MMA(0, 1, At, B1); PG8_BAR; PG8_SCHED;
;             PG8_LDA(At, 0, 1); PG8_STAGE(PG8_SB(0, 0), b2, voffB); PG8_STAGE(PG8_SB(0, 1), b2 + hstep, voffB); PG8_STAGE(PG8_SA(0, 0), a2, voffA);
;             PG8_WAIT_V(8); PG8_WAIT_L(0); PG8_BAR; PG8_MMA(1, 0, At, B0); PG8_MMA(1, 1, At, B1); PG8_BAR; PG8_SCHED;
.Lffout_noz:
	s_waitcnt vmcnt(8)
	s_waitcnt lgkmcnt(0)
	s_barrier
	s_setprio 1
	s_waitcnt lgkmcnt(0)
	v_mfma_f32_16x16x32_bf16 v[142:145], v[114:117], v[180:183], v[142:145]
	v_mfma_f32_16x16x32_bf16 v[138:141], v[122:125], v[180:183], v[138:141]
	v_mfma_f32_16x16x32_bf16 v[110:113], v[114:117], v[192:195], v[110:113]
	v_mfma_f32_16x16x32_bf16 v[106:109], v[122:125], v[192:195], v[106:109]
	v_mfma_f32_16x16x32_bf16 v[94:97], v[114:117], v[200:203], v[94:97]
	v_mfma_f32_16x16x32_bf16 v[90:93], v[122:125], v[200:203], v[90:93]
	v_mfma_f32_16x16x32_bf16 v[78:81], v[114:117], v[208:211], v[78:81]
	v_mfma_f32_16x16x32_bf16 v[74:77], v[122:125], v[208:211], v[74:77]
	v_mfma_f32_16x16x32_bf16 v[142:145], v[118:121], v[188:191], v[142:145]
	v_mfma_f32_16x16x32_bf16 v[138:141], v[134:137], v[188:191], v[138:141]
	v_mfma_f32_16x16x32_bf16 v[110:113], v[118:121], v[196:199], v[110:113]
	v_mfma_f32_16x16x32_bf16 v[106:109], v[134:137], v[196:199], v[106:109]
	v_mfma_f32_16x16x32_bf16 v[94:97], v[118:121], v[204:207], v[94:97]
	v_mfma_f32_16x16x32_bf16 v[90:93], v[134:137], v[204:207], v[90:93]
	v_mfma_f32_16x16x32_bf16 v[78:81], v[118:121], v[212:215], v[78:81]
	v_mfma_f32_16x16x32_bf16 v[74:77], v[134:137], v[212:215], v[74:77]
	v_mfma_f32_16x16x32_bf16 v[130:133], v[146:149], v[180:183], v[130:133]
	v_mfma_f32_16x16x32_bf16 v[126:129], v[166:169], v[180:183], v[126:129]
	v_mfma_f32_16x16x32_bf16 v[102:105], v[146:149], v[192:195], v[102:105]
	v_mfma_f32_16x16x32_bf16 v[98:101], v[166:169], v[192:195], v[98:101]
	v_mfma_f32_16x16x32_bf16 v[86:89], v[146:149], v[200:203], v[86:89]
	v_mfma_f32_16x16x32_bf16 v[82:85], v[166:169], v[200:203], v[82:85]
	v_mfma_f32_16x16x32_bf16 v[70:73], v[146:149], v[208:211], v[70:73]
	v_mfma_f32_16x16x32_bf16 v[66:69], v[166:169], v[208:211], v[66:69]
	v_mfma_f32_16x16x32_bf16 v[130:133], v[150:153], v[188:191], v[130:133]
	v_mfma_f32_16x16x32_bf16 v[126:129], v[170:173], v[188:191], v[126:129]
	v_mfma_f32_16x16x32_bf16 v[102:105], v[150:153], v[196:199], v[102:105]
	v_mfma_f32_16x16x32_bf16 v[98:101], v[170:173], v[196:199], v[98:101]
	v_mfma_f32_16x16x32_bf16 v[86:89], v[150:153], v[204:207], v[86:89]
	v_mfma_f32_16x16x32_bf16 v[82:85], v[170:173], v[204:207], v[82:85]
	v_mfma_f32_16x16x32_bf16 v[70:73], v[150:153], v[212:215], v[70:73]
	v_mfma_f32_16x16x32_bf16 v[66:69], v[170:173], v[212:215], v[66:69]
	s_setprio 0
	s_barrier
	s_add_i32 s22, s51, s34
	v_lshl_add_u64 v[216:217], s[24:25], 0, v[158:159]
	s_mov_b32 m0, s22
	ds_read_b128 v[180:183], v186 offset:16384
	ds_read_b128 v[188:191], v186 offset:17408
	ds_read_b128 v[192:195], v186 offset:18432
	ds_read_b128 v[196:199], v186 offset:19456
	ds_read_b128 v[200:203], v186 offset:20480
	ds_read_b128 v[204:207], v186 offset:21504
	ds_read_b128 v[208:211], v186 offset:22528
	ds_read_b128 v[212:215], v186 offset:23552
	global_load_lds_dwordx4 v[216:217], off
	s_add_i32 m0, s22, 0x2000
	s_add_u32 s22, s24, 0xb0000
	v_lshl_add_u64 v[218:219], s[24:25], 0, v[154:155]
	s_addc_u32 s23, s25, 0
	s_add_i32 s51, s52, s34
	global_load_lds_dwordx4 v[218:219], off
	v_lshl_add_u64 v[220:221], s[22:23], 0, v[158:159]
	s_mov_b32 m0, s51
	v_lshl_add_u64 v[222:223], s[26:27], 0, v[156:157]
	global_load_lds_dwordx4 v[220:221], off
	v_lshl_add_u64 v[220:221], s[22:23], 0, v[154:155]
	s_add_i32 m0, s51, 0x2000
	s_nop 0
	global_load_lds_dwordx4 v[220:221], off
	v_lshl_add_u64 v[220:221], s[26:27], 0, v[160:161]
	s_mov_b32 m0, s35
	s_nop 0
	global_load_lds_dwordx4 v[220:221], off
	s_mov_b32 m0, s36
	s_nop 0
	global_load_lds_dwordx4 v[222:223], off
	s_waitcnt vmcnt(8)
	s_waitcnt lgkmcnt(0)
	s_barrier
	s_setprio 1
	s_waitcnt lgkmcnt(0)
	v_mfma_f32_16x16x32_bf16 v[62:65], v[114:117], v[180:183], v[62:65]
	v_mfma_f32_16x16x32_bf16 v[58:61], v[122:125], v[180:183], v[58:61]
	v_mfma_f32_16x16x32_bf16 v[46:49], v[114:117], v[192:195], v[46:49]
	v_mfma_f32_16x16x32_bf16 v[42:45], v[122:125], v[192:195], v[42:45]
	v_mfma_f32_16x16x32_bf16 v[30:33], v[114:117], v[200:203], v[30:33]
	v_mfma_f32_16x16x32_bf16 v[26:29], v[122:125], v[200:203], v[26:29]
	v_mfma_f32_16x16x32_bf16 v[14:17], v[114:117], v[208:211], v[14:17]
	v_mfma_f32_16x16x32_bf16 v[10:13], v[122:125], v[208:211], v[10:13]
	v_mfma_f32_16x16x32_bf16 v[62:65], v[118:121], v[188:191], v[62:65]
	v_mfma_f32_16x16x32_bf16 v[58:61], v[134:137], v[188:191], v[58:61]
	v_mfma_f32_16x16x32_bf16 v[46:49], v[118:121], v[196:199], v[46:49]
	v_mfma_f32_16x16x32_bf16 v[42:45], v[134:137], v[196:199], v[42:45]
	v_mfma_f32_16x16x32_bf16 v[30:33], v[118:121], v[204:207], v[30:33]
	v_mfma_f32_16x16x32_bf16 v[26:29], v[134:137], v[204:207], v[26:29]
	v_mfma_f32_16x16x32_bf16 v[14:17], v[118:121], v[212:215], v[14:17]
	v_mfma_f32_16x16x32_bf16 v[10:13], v[134:137], v[212:215], v[10:13]
	v_mfma_f32_16x16x32_bf16 v[54:57], v[146:149], v[180:183], v[54:57]
	v_mfma_f32_16x16x32_bf16 v[50:53], v[166:169], v[180:183], v[50:53]
	v_mfma_f32_16x16x32_bf16 v[38:41], v[146:149], v[192:195], v[38:41]
	v_mfma_f32_16x16x32_bf16 v[34:37], v[166:169], v[192:195], v[34:37]
	v_mfma_f32_16x16x32_bf16 v[22:25], v[146:149], v[200:203], v[22:25]
	v_mfma_f32_16x16x32_bf16 v[18:21], v[166:169], v[200:203], v[18:21]
	v_mfma_f32_16x16x32_bf16 v[6:9], v[146:149], v[208:211], v[6:9]
	v_mfma_f32_16x16x32_bf16 v[2:5], v[166:169], v[208:211], v[2:5]
	v_mfma_f32_16x16x32_bf16 v[54:57], v[150:153], v[188:191], v[54:57]
	v_mfma_f32_16x16x32_bf16 v[50:53], v[170:173], v[188:191], v[50:53]
	v_mfma_f32_16x16x32_bf16 v[38:41], v[150:153], v[196:199], v[38:41]
	v_mfma_f32_16x16x32_bf16 v[34:37], v[170:173], v[196:199], v[34:37]
	v_mfma_f32_16x16x32_bf16 v[22:25], v[150:153], v[204:207], v[22:25]
	v_mfma_f32_16x16x32_bf16 v[18:21], v[170:173], v[204:207], v[18:21]
	v_mfma_f32_16x16x32_bf16 v[6:9], v[150:153], v[212:215], v[6:9]
	v_mfma_f32_16x16x32_bf16 v[2:5], v[170:173], v[212:215], v[2:5]
	s_setprio 0
	s_barrier
; #define PG8_STAGE(bufoff, gbase, voff) do { _Pragma("unroll") for (int _i = 0; _i < 2; ++_i) \
;         __builtin_amdgcn_global_load_lds((const unsigned*)((const char*)(gbase) + (voff)[_i]), (PG8_LAS unsigned*)(lds + (bufoff) + ldsw + _i * 8192), 16, 0, 0); } while (0)
; #define PG8_LDA(dst, b, h) do { _Pragma("unroll") for (int m = 0; m < 4; ++m) _Pragma("unroll") for (int k = 0; k < 2; ++k) dst[m][k] = *(const PG8_LAS bf16x8*)(lds + PG8_SA(b, h) + aoff + m * 2048 + k * 1024); } while (0)
; #define PG8_LDB(dst, b, h) do { _Pragma("unroll") for (int n = 0; n < 2; ++n) _Pragma("unroll") for (int k = 0; k < 2; ++k) dst[n][k] = *(const PG8_LAS bf16x8*)(lds + PG8_SB(b, h) + boff + n * 2048 + k * 1024); } while (0)
; #define PG8_MMA(ai, bj, At, Bt) do { __builtin_amdgcn_s_setprio(1); _Pragma("unroll") for (int m = 0; m < 4; ++m) _Pragma("unroll") for (int n = 0; n < 2; ++n) _Pragma("unroll") for (int k = 0; k < 2; ++k) \
;         acc[ai][bj][m][n] = __builtin_amdgcn_mfma_f32_16x16x32_bf16(Bt[n][k], At[m][k], acc[ai][bj][m][n], 0, 0, 0); __builtin_amdgcn_s_setprio(0); } while (0)
; #define PG8_WAIT_V(n) asm volatile("s_waitcnt vmcnt(" #n ")" ::: "memory")
; #define PG8_WAIT_L(n) asm volatile("s_waitcnt lgkmcnt(" #n ")" ::: "memory")
; #define PG8_BAR __builtin_amdgcn_s_barrier()
; #define PG8_SCHED __builtin_amdgcn_sched_barrier(0)
; template <class Epi, class Sched, bool ALIGN_EPI = false, bool SP2 = false>
; __device__ __forceinline__ void gemm_phase(PG8_LAS unsigned char* lds, const Gemm g, const Sched& S, const Epi& E) {
;     ...
;             PG8_LDB(B0, 1, 0); PG8_LDB(B1, 1, 1); PG8_SCHED; PG8_LDA(At, 1, 0); PG8_STAGE(PG8_SA(0, 1), a2 + hstep, voffA);
;             PG8_WAIT_V(8); PG8_WAIT_L(0); PG8_BAR; PG8_MMA(0, 0, At, B0); PG8_MMA(0, 1, At, B1); PG8_BAR; PG8_SCHED;
	s_add_i32 s51, 0, 0x18000
	s_add_i32 s52, 0, 0x1c000
	v_add_u32_e32 v134, s51, v185
	v_add_u32_e32 v170, s52, v185
	ds_read_b128 v[114:117], v134
	ds_read_b128 v[118:121], v134 offset:1024
	ds_read_b128 v[122:125], v134 offset:2048
	ds_read_b128 v[134:137], v134 offset:3072
	ds_read_b128 v[146:149], v170
	ds_read_b128 v[150:153], v170 offset:1024
	ds_read_b128 v[166:169], v170 offset:2048
	ds_read_b128 v[170:173], v170 offset:3072
	s_add_u32 s22, s26, 0xb0000
	s_addc_u32 s23, s27, 0
	s_mov_b32 m0, s37
	v_lshl_add_u64 v[228:229], s[22:23], 0, v[160:161]
	ds_read_b128 v[180:183], v186 offset:32768
	ds_read_b128 v[188:191], v186 offset:33792
	ds_read_b128 v[192:195], v186 offset:34816
	ds_read_b128 v[196:199], v186 offset:35840
	ds_read_b128 v[200:203], v186 offset:36864
	ds_read_b128 v[204:207], v186 offset:37888
	ds_read_b128 v[208:211], v186 offset:38912
	ds_read_b128 v[212:215], v186 offset:39936
	global_load_lds_dwordx4 v[228:229], off
	v_lshl_add_u64 v[228:229], s[22:23], 0, v[156:157]
	s_mov_b32 m0, s38
	s_nop 0
	global_load_lds_dwordx4 v[228:229], off
	s_waitcnt vmcnt(8)
	s_waitcnt lgkmcnt(0)
	s_barrier
	s_setprio 1
	s_waitcnt lgkmcnt(0)
	v_mfma_f32_16x16x32_bf16 v[142:145], v[114:117], v[180:183], v[142:145]
	v_mfma_f32_16x16x32_bf16 v[138:141], v[122:125], v[180:183], v[138:141]
	v_mfma_f32_16x16x32_bf16 v[110:113], v[114:117], v[192:195], v[110:113]
	v_mfma_f32_16x16x32_bf16 v[106:109], v[122:125], v[192:195], v[106:109]
	v_mfma_f32_16x16x32_bf16 v[94:97], v[114:117], v[200:203], v[94:97]
	v_mfma_f32_16x16x32_bf16 v[90:93], v[122:125], v[200:203], v[90:93]
	v_mfma_f32_16x16x32_bf16 v[78:81], v[114:117], v[208:211], v[78:81]
	v_mfma_f32_16x16x32_bf16 v[74:77], v[122:125], v[208:211], v[74:77]
	v_mfma_f32_16x16x32_bf16 v[142:145], v[118:121], v[188:191], v[142:145]
	v_mfma_f32_16x16x32_bf16 v[138:141], v[134:137], v[188:191], v[138:141]
	v_mfma_f32_16x16x32_bf16 v[110:113], v[118:121], v[196:199], v[110:113]
	v_mfma_f32_16x16x32_bf16 v[106:109], v[134:137], v[196:199], v[106:109]
	v_mfma_f32_16x16x32_bf16 v[94:97], v[118:121], v[204:207], v[94:97]
	v_mfma_f32_16x16x32_bf16 v[90:93], v[134:137], v[204:207], v[90:93]
	v_mfma_f32_16x16x32_bf16 v[78:81], v[118:121], v[212:215], v[78:81]
	v_mfma_f32_16x16x32_bf16 v[74:77], v[134:137], v[212:215], v[74:77]
	v_mfma_f32_16x16x32_bf16 v[130:133], v[146:149], v[180:183], v[130:133]
	v_mfma_f32_16x16x32_bf16 v[126:129], v[166:169], v[180:183], v[126:129]
	v_mfma_f32_16x16x32_bf16 v[102:105], v[146:149], v[192:195], v[102:105]
	v_mfma_f32_16x16x32_bf16 v[98:101], v[166:169], v[192:195], v[98:101]
	v_mfma_f32_16x16x32_bf16 v[86:89], v[146:149], v[200:203], v[86:89]
	v_mfma_f32_16x16x32_bf16 v[82:85], v[166:169], v[200:203], v[82:85]
	v_mfma_f32_16x16x32_bf16 v[70:73], v[146:149], v[208:211], v[70:73]
	v_mfma_f32_16x16x32_bf16 v[66:69], v[166:169], v[208:211], v[66:69]
	v_mfma_f32_16x16x32_bf16 v[130:133], v[150:153], v[188:191], v[130:133]
	v_mfma_f32_16x16x32_bf16 v[126:129], v[170:173], v[188:191], v[126:129]
	v_mfma_f32_16x16x32_bf16 v[102:105], v[150:153], v[196:199], v[102:105]
	v_mfma_f32_16x16x32_bf16 v[98:101], v[170:173], v[196:199], v[98:101]
	v_mfma_f32_16x16x32_bf16 v[86:89], v[150:153], v[204:207], v[86:89]
	v_mfma_f32_16x16x32_bf16 v[82:85], v[170:173], v[204:207], v[82:85]
	v_mfma_f32_16x16x32_bf16 v[70:73], v[150:153], v[212:215], v[70:73]
	v_mfma_f32_16x16x32_bf16 v[66:69], v[170:173], v[212:215], v[66:69]
	s_setprio 0
	s_barrier
; #define PG8_STAGE(bufoff, gbase, voff) do { _Pragma("unroll") for (int _i = 0; _i < 2; ++_i) \
;         __builtin_amdgcn_global_load_lds((const unsigned*)((const char*)(gbase) + (voff)[_i]), (PG8_LAS unsigned*)(lds + (bufoff) + ldsw + _i * 8192), 16, 0, 0); } while (0)
; #define PG8_LDA(dst, b, h) do { _Pragma("unroll") for (int m = 0; m < 4; ++m) _Pragma("unroll") for (int k = 0; k < 2; ++k) dst[m][k] = *(const PG8_LAS bf16x8*)(lds + PG8_SA(b, h) + aoff + m * 2048 + k * 1024); } while (0)
; #define PG8_MMA(ai, bj, At, Bt) do { __builtin_amdgcn_s_setprio(1); _Pragma("unroll") for (int m = 0; m < 4; ++m) _Pragma("unroll") for (int n = 0; n < 2; ++n) _Pragma("unroll") for (int k = 0; k < 2; ++k) \
;         acc[ai][bj][m][n] = __builtin_amdgcn_mfma_f32_16x16x32_bf16(Bt[n][k], At[m][k], acc[ai][bj][m][n], 0, 0, 0); __builtin_amdgcn_s_setprio(0); } while (0)
; #define PG8_WAIT_V(n) asm volatile("s_waitcnt vmcnt(" #n ")" ::: "memory")
; #define PG8_WAIT_L(n) asm volatile("s_waitcnt lgkmcnt(" #n ")" ::: "memory")
; #define PG8_BAR __builtin_amdgcn_s_barrier()
; #define PG8_SCHED __builtin_amdgcn_sched_barrier(0)
; template <class Epi, class Sched, bool ALIGN_EPI = false, bool SP2 = false>
; __device__ __forceinline__ void gemm_phase(PG8_LAS unsigned char* lds, const Gemm g, const Sched& S, const Epi& E) {
;     ...
;         for (int t = 0; t < nt; t += 2) {
;     ...
;             PG8_LDA(At, 1, 1); PG8_STAGE(PG8_SB(1, 0), b3, voffB); PG8_STAGE(PG8_SB(1, 1), b3 + hstep, voffB); PG8_STAGE(PG8_SA(1, 0), a3, voffA);
;             PG8_WAIT_V(8); PG8_WAIT_L(0); PG8_BAR; PG8_MMA(1, 0, At, B0); PG8_MMA(1, 1, At, B1); PG8_BAR; PG8_SCHED;
	s_add_i32 s22, s51, s34
	v_lshl_add_u64 v[216:217], v[216:217], 0, s[96:97]
	s_mov_b32 m0, s22
	ds_read_b128 v[180:183], v186 offset:49152
	ds_read_b128 v[188:191], v186 offset:50176
	ds_read_b128 v[192:195], v186 offset:51200
	ds_read_b128 v[196:199], v186 offset:52224
	ds_read_b128 v[200:203], v186 offset:53248
	ds_read_b128 v[204:207], v186 offset:54272
	ds_read_b128 v[208:211], v186 offset:55296
	ds_read_b128 v[212:215], v186 offset:56320
	global_load_lds_dwordx4 v[216:217], off
	s_add_i32 m0, s22, 0x2000
	s_add_u32 s22, s24, 0xb0080
	v_lshl_add_u64 v[216:217], v[218:219], 0, s[96:97]
	s_addc_u32 s23, s25, 0
	s_add_i32 s24, s52, s34
	global_load_lds_dwordx4 v[216:217], off
	v_lshl_add_u64 v[216:217], s[22:23], 0, v[158:159]
	s_mov_b32 m0, s24
	s_nop 0
	global_load_lds_dwordx4 v[216:217], off
	v_lshl_add_u64 v[216:217], s[22:23], 0, v[154:155]
	s_add_i32 m0, s24, 0x2000
	s_nop 0
	global_load_lds_dwordx4 v[216:217], off
	v_lshl_add_u64 v[216:217], v[220:221], 0, s[96:97]
	s_mov_b32 m0, s41
	s_nop 0
	global_load_lds_dwordx4 v[216:217], off
	v_lshl_add_u64 v[216:217], v[222:223], 0, s[96:97]
	s_mov_b32 m0, s42
	s_nop 0
	global_load_lds_dwordx4 v[216:217], off
	s_waitcnt vmcnt(8)
	s_waitcnt lgkmcnt(0)
	s_barrier
	s_setprio 1
	s_waitcnt lgkmcnt(0)
	v_mfma_f32_16x16x32_bf16 v[62:65], v[114:117], v[180:183], v[62:65]
	v_mfma_f32_16x16x32_bf16 v[58:61], v[122:125], v[180:183], v[58:61]
	v_mfma_f32_16x16x32_bf16 v[46:49], v[114:117], v[192:195], v[46:49]
	v_mfma_f32_16x16x32_bf16 v[42:45], v[122:125], v[192:195], v[42:45]
	v_mfma_f32_16x16x32_bf16 v[30:33], v[114:117], v[200:203], v[30:33]
	v_mfma_f32_16x16x32_bf16 v[26:29], v[122:125], v[200:203], v[26:29]
	v_mfma_f32_16x16x32_bf16 v[14:17], v[114:117], v[208:211], v[14:17]
	v_mfma_f32_16x16x32_bf16 v[10:13], v[122:125], v[208:211], v[10:13]
	v_mfma_f32_16x16x32_bf16 v[62:65], v[118:121], v[188:191], v[62:65]
	v_mfma_f32_16x16x32_bf16 v[58:61], v[134:137], v[188:191], v[58:61]
	v_mfma_f32_16x16x32_bf16 v[46:49], v[118:121], v[196:199], v[46:49]
	v_mfma_f32_16x16x32_bf16 v[42:45], v[134:137], v[196:199], v[42:45]
	v_mfma_f32_16x16x32_bf16 v[30:33], v[118:121], v[204:207], v[30:33]
	v_mfma_f32_16x16x32_bf16 v[26:29], v[134:137], v[204:207], v[26:29]
	v_mfma_f32_16x16x32_bf16 v[14:17], v[118:121], v[212:215], v[14:17]
	v_mfma_f32_16x16x32_bf16 v[10:13], v[134:137], v[212:215], v[10:13]
	v_mfma_f32_16x16x32_bf16 v[54:57], v[146:149], v[180:183], v[54:57]
	v_mfma_f32_16x16x32_bf16 v[50:53], v[166:169], v[180:183], v[50:53]
	v_mfma_f32_16x16x32_bf16 v[38:41], v[146:149], v[192:195], v[38:41]
	v_mfma_f32_16x16x32_bf16 v[34:37], v[166:169], v[192:195], v[34:37]
	v_mfma_f32_16x16x32_bf16 v[22:25], v[146:149], v[200:203], v[22:25]
	v_mfma_f32_16x16x32_bf16 v[18:21], v[166:169], v[200:203], v[18:21]
	v_mfma_f32_16x16x32_bf16 v[6:9], v[146:149], v[208:211], v[6:9]
	v_mfma_f32_16x16x32_bf16 v[2:5], v[166:169], v[208:211], v[2:5]
	v_mfma_f32_16x16x32_bf16 v[54:57], v[150:153], v[188:191], v[54:57]
	v_mfma_f32_16x16x32_bf16 v[50:53], v[170:173], v[188:191], v[50:53]
	v_mfma_f32_16x16x32_bf16 v[38:41], v[150:153], v[196:199], v[38:41]
	v_mfma_f32_16x16x32_bf16 v[34:37], v[170:173], v[196:199], v[34:37]
	v_mfma_f32_16x16x32_bf16 v[22:25], v[150:153], v[204:207], v[22:25]
	v_mfma_f32_16x16x32_bf16 v[18:21], v[170:173], v[204:207], v[18:21]
	v_mfma_f32_16x16x32_bf16 v[6:9], v[150:153], v[212:215], v[6:9]
	v_mfma_f32_16x16x32_bf16 v[2:5], v[170:173], v[212:215], v[2:5]
	s_setprio 0
	s_barrier
	s_add_i32 s50, s50, 2
	s_add_u32 s33, s33, 0x100
	s_addc_u32 s49, s49, 0
	s_cmp_gt_u32 s50, 41
	s_mov_b64 s[22:23], s[8:9]
	s_cbranch_scc0 .LBB0_1360
	s_and_b64 vcc, exec, s[14:15]
	s_cbranch_vccz .LBB0_1363
	s_barrier
